# first-iteration vmcnt relaxation after the tile epilogue also in the last Down GEMM and the Out GEMM
# speedup vs baseline: 1.0000x; 1.0000x over previous
; #define PG8_STAGE(bufoff, gbase, voff) do { _Pragma("unroll") for (int _i = 0; _i < 2; ++_i) \
;         __builtin_amdgcn_global_load_lds((const unsigned*)((const char*)(gbase) + (voff)[_i]), (PG8_LAS unsigned*)(lds + (bufoff) + ldsw + _i * 8192), 16, 0, 0); } while (0)
; #define PG8_WAIT_V(n) asm volatile("s_waitcnt vmcnt(" #n ")" ::: "memory")
; #define PG8_BAR __builtin_amdgcn_s_barrier()
; template <class Epi, class Sched, bool ALIGN_EPI = false, bool SP2 = false>
; __device__ __forceinline__ void gemm_phase(PG8_LAS unsigned char* lds, const Gemm g, const Sched& S, const Epi& E) {
;     ...
;     for (int i = 0; i < 2; ++i) { int R, C; stage_rc(tid * 16 + i * 8192, R, C); const int Rb = Epi::PERM ? ((R & ~31) + perm32(R & 31)) : R;
;         voffA[i] = (unsigned)(R * K + C) * 2u; voffB[i] = (unsigned)(Rb * K + C) * 2u; }
;     const size_t kstep = (size_t)(BK * 2);
;     const size_t hstep = (size_t)HALF * K * 2;
;     const size_t tstep = 2 * hstep;
;     const unsigned ldsw = (unsigned)wid * 1024u;
;     const int aoff = lds_byte(wr * 64 + fr, fq * 8), boff = lds_byte(wc * 32 + fr, fq * 8);
;     ...
;     Unit cur, nxt; int ui = 0;
;     if (!S.next(0, cur)) return;
;     f32x4 acc[2][2][4][2];
; #pragma unroll
;     for (int a = 0; a < 2; ++a)
; #pragma unroll
;         for (int b = 0; b < 2; ++b)
; #pragma unroll
;             for (int m = 0; m < 4; ++m)
; #pragma unroll
;                 for (int n = 0; n < 2; ++n) acc[a][b][m][n] = (f32x4){0.f, 0.f, 0.f, 0.f};
;     bf16x8 At[4][2], B0[2][2], B1[2][2];
;     const char* cA = (const char*)g.A + (size_t)cur.pm * tstep; const char* cB = (const char*)g.Bt + (size_t)cur.pn * tstep;
;     S.a_ready(cur);
;     if constexpr (SP2) {
;         PG8_STAGE(PG8_SB(0, 0), cB, voffB); PG8_STAGE(PG8_SB(0, 1), cB + hstep, voffB); PG8_STAGE(PG8_SA(0, 0), cA, voffA); PG8_STAGE(PG8_SA(0, 1), cA + hstep, voffA);
;         if (wr == 1) PG8_BAR;
;         PG8_WAIT_V(2); PG8_BAR;
;         PG8_STAGE(PG8_SB(1, 0), cB + kstep, voffB); PG8_STAGE(PG8_SA(1, 0), cA + kstep, voffA); PG8_STAGE(PG8_SB(1, 1), cB + hstep + kstep, voffB);
;         PG8_WAIT_V(6); PG8_BAR;
.LBB0_374:
	s_lshl_b32 s53, s0, 6
	s_lshl_b32 s5, s0, 13
	s_lshl_b32 s0, s1, 5
	s_and_b32 s60, s0, 0x60
	s_add_i32 m0, s39, 0x18000
	v_lshl_add_u64 v[8:9], v[8:9], 0, s[28:29]
	s_lshl_b32 s8, s60, 7
	s_waitcnt vmcnt(2)
	s_barrier
	global_load_lds_dwordx4 v[8:9], off
	v_lshl_add_u64 v[6:7], v[6:7], 0, s[28:29]
	s_add_i32 m0, s39, 0x1a000
	s_add_i32 s61, s39, 0x8000
	s_add_i32 s64, s39, 0xa000
	global_load_lds_dwordx4 v[6:7], off
	v_lshl_add_u64 v[2:3], v[2:3], 0, s[28:29]
	s_mov_b32 m0, s61
	s_add_u32 s0, s24, 0xb0080
	global_load_lds_dwordx4 v[2:3], off
	v_lshl_add_u64 v[2:3], v[4:5], 0, s[28:29]
	s_mov_b32 m0, s64
	s_addc_u32 s1, s25, 0
	global_load_lds_dwordx4 v[2:3], off
	s_add_i32 m0, s39, 0x1c000
	v_lshl_add_u64 v[2:3], s[0:1], 0, v[180:181]
	global_load_lds_dwordx4 v[2:3], off
	v_lshl_add_u64 v[2:3], s[0:1], 0, v[184:185]
	s_add_i32 m0, s39, 0x1e000
	s_movk_i32 s0, 0x3c0
	global_load_lds_dwordx4 v[2:3], off
	v_and_b32_e32 v2, 48, v0
	v_lshlrev_b32_e32 v3, 6, v0
	v_lshlrev_b32_e32 v0, 2, v0
	v_and_or_b32 v2, v3, s0, v2
	v_and_b32_e32 v0, 32, v0
	s_cmpk_lt_u32 s4, 0x100
	s_movk_i32 s4, 0xb00
	v_bitop3_b32 v4, v2, s5, v0 bitop3:0xde
	v_bitop3_b32 v204, s8, v2, v0 bitop3:0xf6
	v_lshrrev_b32_e32 v2, 1, v14
	v_mul_lo_u32 v0, v16, s4
	s_mov_b32 s5, 0xb000
	v_mad_u64_u32 v[2:3], s[0:1], v2, s5, v[0:1]
	v_or_b32_e32 v0, v2, v15
	v_add_lshl_u32 v0, v0, v17, 1
	s_mov_b64 s[14:15], 0xb0080
	v_lshl_add_u64 v[186:187], v[0:1], 0, s[14:15]
	v_lshrrev_b32_e32 v2, 1, v10
	v_mul_lo_u32 v0, v12, s4
	v_mad_u64_u32 v[2:3], s[0:1], v2, s5, v[0:1]
	s_waitcnt vmcnt(6)
	v_or_b32_e32 v0, v2, v11
	v_add_lshl_u32 v0, v0, v13, 1
	s_cselect_b64 s[8:9], -1, 0
	v_lshl_add_u64 v[188:189], v[0:1], 0, s[14:15]
	s_mov_b32 s65, 0
	v_add_u32_e32 v205, 0, v4
	s_barrier
	s_mov_b32 s98, 0
	s_branch .LBB0_377

; #define PG8_STAGE(bufoff, gbase, voff) do { _Pragma("unroll") for (int _i = 0; _i < 2; ++_i) \
;         __builtin_amdgcn_global_load_lds((const unsigned*)((const char*)(gbase) + (voff)[_i]), (PG8_LAS unsigned*)(lds + (bufoff) + ldsw + _i * 8192), 16, 0, 0); } while (0)
; #define PG8_LDA(dst, b, h) do { _Pragma("unroll") for (int m = 0; m < 4; ++m) _Pragma("unroll") for (int k = 0; k < 2; ++k) dst[m][k] = *(const PG8_LAS bf16x8*)(lds + PG8_SA(b, h) + aoff + m * 2048 + k * 1024); } while (0)
; #define PG8_LDB(dst, b, h) do { _Pragma("unroll") for (int n = 0; n < 2; ++n) _Pragma("unroll") for (int k = 0; k < 2; ++k) dst[n][k] = *(const PG8_LAS bf16x8*)(lds + PG8_SB(b, h) + boff + n * 2048 + k * 1024); } while (0)
; #define PG8_MMA(ai, bj, At, Bt) do { __builtin_amdgcn_s_setprio(1); _Pragma("unroll") for (int m = 0; m < 4; ++m) _Pragma("unroll") for (int n = 0; n < 2; ++n) _Pragma("unroll") for (int k = 0; k < 2; ++k) \
;         acc[ai][bj][m][n] = __builtin_amdgcn_mfma_f32_16x16x32_bf16(Bt[n][k], At[m][k], acc[ai][bj][m][n], 0, 0, 0); __builtin_amdgcn_s_setprio(0); } while (0)
; #define PG8_WAIT_V(n) asm volatile("s_waitcnt vmcnt(" #n ")" ::: "memory")
; #define PG8_WAIT_L(n) asm volatile("s_waitcnt lgkmcnt(" #n ")" ::: "memory")
; #define PG8_BAR __builtin_amdgcn_s_barrier()
; #define PG8_SCHED __builtin_amdgcn_sched_barrier(0)
; template <class Epi, class Sched, bool ALIGN_EPI = false, bool SP2 = false>
; __device__ __forceinline__ void gemm_phase(PG8_LAS unsigned char* lds, const Gemm g, const Sched& S, const Epi& E) {
;     ...
;             PG8_LDB(B0, 0, 0); PG8_LDB(B1, 0, 1); PG8_SCHED; PG8_LDA(At, 0, 0); PG8_STAGE(PG8_SA(1, 1), a1 + hstep, voffA);
;             PG8_WAIT_V(8); PG8_WAIT_L(0); PG8_BAR; PG8_MMA(0, 0, At, B0); PG8_MMA(0, 1, At, B1); PG8_BAR; PG8_SCHED;
;             PG8_LDA(At, 0, 1); PG8_STAGE(PG8_SB(0, 0), b2, voffB); PG8_STAGE(PG8_SB(0, 1), b2 + hstep, voffB); PG8_STAGE(PG8_SA(0, 0), a2, voffA);
;             PG8_WAIT_V(8); PG8_WAIT_L(0); PG8_BAR; PG8_MMA(1, 0, At, B0); PG8_MMA(1, 1, At, B1); PG8_BAR; PG8_SCHED;
.LBB0_388:
	s_add_u32 s24, s22, 0x100
	s_addc_u32 s25, s23, 0
	s_add_i32 s77, 0, 0x10000
	s_cmp_eq_u32 s76, 40
	s_cselect_b32 s37, s5, s25
	s_cselect_b32 s36, s4, s24
	v_add_u32_e32 v0, s77, v204
	s_cselect_b32 s27, s15, s75
	s_cselect_b32 s26, s14, s74
	s_add_i32 s78, 0, 0x14000
	ds_read_b128 v[130:133], v0
	ds_read_b128 v[134:137], v0 offset:1024
	ds_read_b128 v[138:141], v0 offset:2048
	ds_read_b128 v[142:145], v0 offset:3072
	v_add_u32_e32 v0, s78, v204
	ds_read_b128 v[146:149], v0
	ds_read_b128 v[150:153], v0 offset:1024
	ds_read_b128 v[154:157], v0 offset:2048
	ds_read_b128 v[158:161], v0 offset:3072
	v_lshl_add_u64 v[202:203], s[22:23], 0, v[188:189]
	s_add_i32 m0, s39, 0xc000
	ds_read_b128 v[162:165], v205
	ds_read_b128 v[166:169], v205 offset:1024
	ds_read_b128 v[170:173], v205 offset:2048
	ds_read_b128 v[174:177], v205 offset:3072
	ds_read_b128 v[190:193], v205 offset:4096
	ds_read_b128 v[194:197], v205 offset:5120
	ds_read_b128 v[198:201], v205 offset:6144
	ds_read_b128 v[206:209], v205 offset:7168
	global_load_lds_dwordx4 v[202:203], off
	v_lshl_add_u64 v[202:203], s[22:23], 0, v[186:187]
	s_add_i32 m0, s39, 0xe000
	s_nop 0
	global_load_lds_dwordx4 v[202:203], off
	s_cmp_lg_u32 s98, 0
	s_cbranch_scc1 .Lrw_dl_1
	s_waitcnt vmcnt(8)
.Lrw_dl_1:
	s_waitcnt lgkmcnt(0)
	s_barrier
	s_setprio 1
	s_waitcnt lgkmcnt(0)
	v_mfma_f32_16x16x32_bf16 v[126:129], v[130:133], v[162:165], v[126:129]
	v_mfma_f32_16x16x32_bf16 v[122:125], v[138:141], v[162:165], v[122:125]
	v_mfma_f32_16x16x32_bf16 v[118:121], v[130:133], v[170:173], v[118:121]
	v_mfma_f32_16x16x32_bf16 v[110:113], v[138:141], v[170:173], v[110:113]
	v_mfma_f32_16x16x32_bf16 v[102:105], v[130:133], v[190:193], v[102:105]
	v_mfma_f32_16x16x32_bf16 v[94:97], v[138:141], v[190:193], v[94:97]
	v_mfma_f32_16x16x32_bf16 v[78:81], v[130:133], v[198:201], v[78:81]
	v_mfma_f32_16x16x32_bf16 v[74:77], v[138:141], v[198:201], v[74:77]
	v_mfma_f32_16x16x32_bf16 v[126:129], v[134:137], v[166:169], v[126:129]
	v_mfma_f32_16x16x32_bf16 v[122:125], v[142:145], v[166:169], v[122:125]
	v_mfma_f32_16x16x32_bf16 v[118:121], v[134:137], v[174:177], v[118:121]
	v_mfma_f32_16x16x32_bf16 v[110:113], v[142:145], v[174:177], v[110:113]
	v_mfma_f32_16x16x32_bf16 v[102:105], v[134:137], v[194:197], v[102:105]
	v_mfma_f32_16x16x32_bf16 v[94:97], v[142:145], v[194:197], v[94:97]
	v_mfma_f32_16x16x32_bf16 v[78:81], v[134:137], v[206:209], v[78:81]
	v_mfma_f32_16x16x32_bf16 v[74:77], v[142:145], v[206:209], v[74:77]
	s_setprio 0
	s_setprio 1
	v_mfma_f32_16x16x32_bf16 v[114:117], v[146:149], v[162:165], v[114:117]
	v_mfma_f32_16x16x32_bf16 v[106:109], v[154:157], v[162:165], v[106:109]
	v_mfma_f32_16x16x32_bf16 v[98:101], v[146:149], v[170:173], v[98:101]
	v_mfma_f32_16x16x32_bf16 v[90:93], v[154:157], v[170:173], v[90:93]
	v_mfma_f32_16x16x32_bf16 v[86:89], v[146:149], v[190:193], v[86:89]
	v_mfma_f32_16x16x32_bf16 v[82:85], v[154:157], v[190:193], v[82:85]
	v_mfma_f32_16x16x32_bf16 v[70:73], v[146:149], v[198:201], v[70:73]
	v_mfma_f32_16x16x32_bf16 v[66:69], v[154:157], v[198:201], v[66:69]
	v_mfma_f32_16x16x32_bf16 v[114:117], v[150:153], v[166:169], v[114:117]
	v_mfma_f32_16x16x32_bf16 v[106:109], v[158:161], v[166:169], v[106:109]
	v_mfma_f32_16x16x32_bf16 v[98:101], v[150:153], v[174:177], v[98:101]
	v_mfma_f32_16x16x32_bf16 v[90:93], v[158:161], v[174:177], v[90:93]
	v_mfma_f32_16x16x32_bf16 v[86:89], v[150:153], v[194:197], v[86:89]
	v_mfma_f32_16x16x32_bf16 v[82:85], v[158:161], v[194:197], v[82:85]
	v_mfma_f32_16x16x32_bf16 v[70:73], v[150:153], v[206:209], v[70:73]
	v_mfma_f32_16x16x32_bf16 v[66:69], v[158:161], v[206:209], v[66:69]
	s_setprio 0
	s_barrier
	s_add_i32 s22, s77, s38
	v_lshl_add_u64 v[202:203], s[26:27], 0, v[180:181]
	s_mov_b32 m0, s22
	ds_read_b128 v[162:165], v205 offset:16384
	ds_read_b128 v[166:169], v205 offset:17408
	ds_read_b128 v[170:173], v205 offset:18432
	ds_read_b128 v[174:177], v205 offset:19456
	ds_read_b128 v[190:193], v205 offset:20480
	ds_read_b128 v[194:197], v205 offset:21504
	ds_read_b128 v[198:201], v205 offset:22528
	ds_read_b128 v[206:209], v205 offset:23552
	global_load_lds_dwordx4 v[202:203], off
	s_add_i32 m0, s22, 0x2000
	s_add_u32 s22, s26, 0xb0000
	v_lshl_add_u64 v[210:211], s[26:27], 0, v[184:185]
	s_addc_u32 s23, s27, 0
	s_add_i32 s77, s78, s38
	global_load_lds_dwordx4 v[210:211], off
	v_lshl_add_u64 v[220:221], s[22:23], 0, v[180:181]
	s_mov_b32 m0, s77
	v_lshl_add_u64 v[222:223], s[36:37], 0, v[182:183]
	global_load_lds_dwordx4 v[220:221], off
	v_lshl_add_u64 v[220:221], s[22:23], 0, v[184:185]
	s_add_i32 m0, s77, 0x2000
	s_nop 0
	global_load_lds_dwordx4 v[220:221], off
	v_lshl_add_u64 v[220:221], s[36:37], 0, v[178:179]
	s_mov_b32 m0, s39
	s_nop 0
	global_load_lds_dwordx4 v[220:221], off
	s_mov_b32 m0, s40
	s_nop 0
	global_load_lds_dwordx4 v[222:223], off
	s_cmp_lg_u32 s98, 0
	s_cbranch_scc1 .Lrw_dl_2
	s_waitcnt vmcnt(8)
; #define PG8_STAGE(bufoff, gbase, voff) do { _Pragma("unroll") for (int _i = 0; _i < 2; ++_i) \
;         __builtin_amdgcn_global_load_lds((const unsigned*)((const char*)(gbase) + (voff)[_i]), (PG8_LAS unsigned*)(lds + (bufoff) + ldsw + _i * 8192), 16, 0, 0); } while (0)
; #define PG8_LDA(dst, b, h) do { _Pragma("unroll") for (int m = 0; m < 4; ++m) _Pragma("unroll") for (int k = 0; k < 2; ++k) dst[m][k] = *(const PG8_LAS bf16x8*)(lds + PG8_SA(b, h) + aoff + m * 2048 + k * 1024); } while (0)
; #define PG8_LDB(dst, b, h) do { _Pragma("unroll") for (int n = 0; n < 2; ++n) _Pragma("unroll") for (int k = 0; k < 2; ++k) dst[n][k] = *(const PG8_LAS bf16x8*)(lds + PG8_SB(b, h) + boff + n * 2048 + k * 1024); } while (0)
; #define PG8_MMA(ai, bj, At, Bt) do { __builtin_amdgcn_s_setprio(1); _Pragma("unroll") for (int m = 0; m < 4; ++m) _Pragma("unroll") for (int n = 0; n < 2; ++n) _Pragma("unroll") for (int k = 0; k < 2; ++k) \
;         acc[ai][bj][m][n] = __builtin_amdgcn_mfma_f32_16x16x32_bf16(Bt[n][k], At[m][k], acc[ai][bj][m][n], 0, 0, 0); __builtin_amdgcn_s_setprio(0); } while (0)
; #define PG8_WAIT_V(n) asm volatile("s_waitcnt vmcnt(" #n ")" ::: "memory")
; #define PG8_WAIT_L(n) asm volatile("s_waitcnt lgkmcnt(" #n ")" ::: "memory")
; #define PG8_BAR __builtin_amdgcn_s_barrier()
; #define PG8_SCHED __builtin_amdgcn_sched_barrier(0)
; template <class Epi, class Sched, bool ALIGN_EPI = false, bool SP2 = false>
; __device__ __forceinline__ void gemm_phase(PG8_LAS unsigned char* lds, const Gemm g, const Sched& S, const Epi& E) {
;     ...
;             PG8_WAIT_V(8); PG8_WAIT_L(0); PG8_BAR; PG8_MMA(1, 0, At, B0); PG8_MMA(1, 1, At, B1); PG8_BAR; PG8_SCHED;
;             PG8_LDB(B0, 1, 0); PG8_LDB(B1, 1, 1); PG8_SCHED; PG8_LDA(At, 1, 0); PG8_STAGE(PG8_SA(0, 1), a2 + hstep, voffA);
;             PG8_WAIT_V(8); PG8_WAIT_L(0); PG8_BAR; PG8_MMA(0, 0, At, B0); PG8_MMA(0, 1, At, B1); PG8_BAR; PG8_SCHED;
.Lrw_dl_2:
	s_mov_b32 s98, 0
	s_waitcnt lgkmcnt(0)
	s_barrier
	s_setprio 1
	s_waitcnt lgkmcnt(0)
	v_mfma_f32_16x16x32_bf16 v[62:65], v[130:133], v[162:165], v[62:65]
	v_mfma_f32_16x16x32_bf16 v[58:61], v[138:141], v[162:165], v[58:61]
	v_mfma_f32_16x16x32_bf16 v[54:57], v[130:133], v[170:173], v[54:57]
	v_mfma_f32_16x16x32_bf16 v[46:49], v[138:141], v[170:173], v[46:49]
	v_mfma_f32_16x16x32_bf16 v[38:41], v[130:133], v[190:193], v[38:41]
	v_mfma_f32_16x16x32_bf16 v[30:33], v[138:141], v[190:193], v[30:33]
	v_mfma_f32_16x16x32_bf16 v[14:17], v[130:133], v[198:201], v[14:17]
	v_mfma_f32_16x16x32_bf16 v[10:13], v[138:141], v[198:201], v[10:13]
	v_mfma_f32_16x16x32_bf16 v[62:65], v[134:137], v[166:169], v[62:65]
	v_mfma_f32_16x16x32_bf16 v[58:61], v[142:145], v[166:169], v[58:61]
	v_mfma_f32_16x16x32_bf16 v[54:57], v[134:137], v[174:177], v[54:57]
	v_mfma_f32_16x16x32_bf16 v[46:49], v[142:145], v[174:177], v[46:49]
	v_mfma_f32_16x16x32_bf16 v[38:41], v[134:137], v[194:197], v[38:41]
	v_mfma_f32_16x16x32_bf16 v[30:33], v[142:145], v[194:197], v[30:33]
	v_mfma_f32_16x16x32_bf16 v[14:17], v[134:137], v[206:209], v[14:17]
	v_mfma_f32_16x16x32_bf16 v[10:13], v[142:145], v[206:209], v[10:13]
	s_setprio 0
	s_setprio 1
	v_mfma_f32_16x16x32_bf16 v[50:53], v[146:149], v[162:165], v[50:53]
	v_mfma_f32_16x16x32_bf16 v[42:45], v[154:157], v[162:165], v[42:45]
	v_mfma_f32_16x16x32_bf16 v[34:37], v[146:149], v[170:173], v[34:37]
	v_mfma_f32_16x16x32_bf16 v[26:29], v[154:157], v[170:173], v[26:29]
	v_mfma_f32_16x16x32_bf16 v[22:25], v[146:149], v[190:193], v[22:25]
	v_mfma_f32_16x16x32_bf16 v[18:21], v[154:157], v[190:193], v[18:21]
	v_mfma_f32_16x16x32_bf16 v[6:9], v[146:149], v[198:201], v[6:9]
	v_mfma_f32_16x16x32_bf16 v[2:5], v[154:157], v[198:201], v[2:5]
	v_mfma_f32_16x16x32_bf16 v[50:53], v[150:153], v[166:169], v[50:53]
	v_mfma_f32_16x16x32_bf16 v[42:45], v[158:161], v[166:169], v[42:45]
	v_mfma_f32_16x16x32_bf16 v[34:37], v[150:153], v[174:177], v[34:37]
	v_mfma_f32_16x16x32_bf16 v[26:29], v[158:161], v[174:177], v[26:29]
	v_mfma_f32_16x16x32_bf16 v[22:25], v[150:153], v[194:197], v[22:25]
	v_mfma_f32_16x16x32_bf16 v[18:21], v[158:161], v[194:197], v[18:21]
	v_mfma_f32_16x16x32_bf16 v[6:9], v[150:153], v[206:209], v[6:9]
	v_mfma_f32_16x16x32_bf16 v[2:5], v[158:161], v[206:209], v[2:5]
	s_setprio 0
	s_barrier
	s_add_i32 s77, 0, 0x18000
	v_add_u32_e32 v0, s77, v204
	s_add_i32 s78, 0, 0x1c000
	ds_read_b128 v[130:133], v0
	ds_read_b128 v[134:137], v0 offset:1024
	ds_read_b128 v[138:141], v0 offset:2048
	ds_read_b128 v[142:145], v0 offset:3072
	v_add_u32_e32 v0, s78, v204
	ds_read_b128 v[146:149], v0
	ds_read_b128 v[150:153], v0 offset:1024
	ds_read_b128 v[154:157], v0 offset:2048
	ds_read_b128 v[158:161], v0 offset:3072
	s_add_u32 s22, s36, 0xb0000
	s_addc_u32 s23, s37, 0
	s_mov_b32 m0, s41
	v_lshl_add_u64 v[224:225], s[22:23], 0, v[178:179]
	ds_read_b128 v[162:165], v205 offset:32768
	ds_read_b128 v[166:169], v205 offset:33792
	ds_read_b128 v[170:173], v205 offset:34816
	ds_read_b128 v[174:177], v205 offset:35840
	ds_read_b128 v[190:193], v205 offset:36864
	ds_read_b128 v[194:197], v205 offset:37888
	ds_read_b128 v[198:201], v205 offset:38912
	ds_read_b128 v[206:209], v205 offset:39936
	global_load_lds_dwordx4 v[224:225], off
	v_lshl_add_u64 v[224:225], s[22:23], 0, v[182:183]
	s_mov_b32 m0, s52
	s_nop 0
	global_load_lds_dwordx4 v[224:225], off
	s_waitcnt vmcnt(8)
	s_waitcnt lgkmcnt(0)
	s_barrier
	s_setprio 1
	s_waitcnt lgkmcnt(0)
	v_mfma_f32_16x16x32_bf16 v[126:129], v[130:133], v[162:165], v[126:129]
	v_mfma_f32_16x16x32_bf16 v[122:125], v[138:141], v[162:165], v[122:125]
	v_mfma_f32_16x16x32_bf16 v[118:121], v[130:133], v[170:173], v[118:121]
	v_mfma_f32_16x16x32_bf16 v[110:113], v[138:141], v[170:173], v[110:113]
	v_mfma_f32_16x16x32_bf16 v[102:105], v[130:133], v[190:193], v[102:105]
	v_mfma_f32_16x16x32_bf16 v[94:97], v[138:141], v[190:193], v[94:97]
	v_mfma_f32_16x16x32_bf16 v[78:81], v[130:133], v[198:201], v[78:81]
	v_mfma_f32_16x16x32_bf16 v[74:77], v[138:141], v[198:201], v[74:77]
	v_mfma_f32_16x16x32_bf16 v[126:129], v[134:137], v[166:169], v[126:129]
	v_mfma_f32_16x16x32_bf16 v[122:125], v[142:145], v[166:169], v[122:125]
	v_mfma_f32_16x16x32_bf16 v[118:121], v[134:137], v[174:177], v[118:121]
	v_mfma_f32_16x16x32_bf16 v[110:113], v[142:145], v[174:177], v[110:113]
	v_mfma_f32_16x16x32_bf16 v[102:105], v[134:137], v[194:197], v[102:105]
	v_mfma_f32_16x16x32_bf16 v[94:97], v[142:145], v[194:197], v[94:97]
	v_mfma_f32_16x16x32_bf16 v[78:81], v[134:137], v[206:209], v[78:81]
	v_mfma_f32_16x16x32_bf16 v[74:77], v[142:145], v[206:209], v[74:77]
	s_setprio 0
	s_setprio 1
	v_mfma_f32_16x16x32_bf16 v[114:117], v[146:149], v[162:165], v[114:117]
	v_mfma_f32_16x16x32_bf16 v[106:109], v[154:157], v[162:165], v[106:109]
	v_mfma_f32_16x16x32_bf16 v[98:101], v[146:149], v[170:173], v[98:101]
	v_mfma_f32_16x16x32_bf16 v[90:93], v[154:157], v[170:173], v[90:93]
	v_mfma_f32_16x16x32_bf16 v[86:89], v[146:149], v[190:193], v[86:89]
	v_mfma_f32_16x16x32_bf16 v[82:85], v[154:157], v[190:193], v[82:85]
	v_mfma_f32_16x16x32_bf16 v[70:73], v[146:149], v[198:201], v[70:73]
	v_mfma_f32_16x16x32_bf16 v[66:69], v[154:157], v[198:201], v[66:69]
	v_mfma_f32_16x16x32_bf16 v[114:117], v[150:153], v[166:169], v[114:117]
	v_mfma_f32_16x16x32_bf16 v[106:109], v[158:161], v[166:169], v[106:109]
	v_mfma_f32_16x16x32_bf16 v[98:101], v[150:153], v[174:177], v[98:101]
	v_mfma_f32_16x16x32_bf16 v[90:93], v[158:161], v[174:177], v[90:93]
	v_mfma_f32_16x16x32_bf16 v[86:89], v[150:153], v[194:197], v[86:89]
	v_mfma_f32_16x16x32_bf16 v[82:85], v[158:161], v[194:197], v[82:85]
	v_mfma_f32_16x16x32_bf16 v[70:73], v[150:153], v[206:209], v[70:73]
	v_mfma_f32_16x16x32_bf16 v[66:69], v[158:161], v[206:209], v[66:69]
	s_setprio 0
	s_barrier
; #define PG8_STAGE(bufoff, gbase, voff) do { _Pragma("unroll") for (int _i = 0; _i < 2; ++_i) \
;         __builtin_amdgcn_global_load_lds((const unsigned*)((const char*)(gbase) + (voff)[_i]), (PG8_LAS unsigned*)(lds + (bufoff) + ldsw + _i * 8192), 16, 0, 0); } while (0)
; #define PG8_LDA(dst, b, h) do { _Pragma("unroll") for (int m = 0; m < 4; ++m) _Pragma("unroll") for (int k = 0; k < 2; ++k) dst[m][k] = *(const PG8_LAS bf16x8*)(lds + PG8_SA(b, h) + aoff + m * 2048 + k * 1024); } while (0)
; #define PG8_MMA(ai, bj, At, Bt) do { __builtin_amdgcn_s_setprio(1); _Pragma("unroll") for (int m = 0; m < 4; ++m) _Pragma("unroll") for (int n = 0; n < 2; ++n) _Pragma("unroll") for (int k = 0; k < 2; ++k) \
;         acc[ai][bj][m][n] = __builtin_amdgcn_mfma_f32_16x16x32_bf16(Bt[n][k], At[m][k], acc[ai][bj][m][n], 0, 0, 0); __builtin_amdgcn_s_setprio(0); } while (0)
; #define PG8_WAIT_V(n) asm volatile("s_waitcnt vmcnt(" #n ")" ::: "memory")
; #define PG8_WAIT_L(n) asm volatile("s_waitcnt lgkmcnt(" #n ")" ::: "memory")
; #define PG8_BAR __builtin_amdgcn_s_barrier()
; #define PG8_SCHED __builtin_amdgcn_sched_barrier(0)
;     __device__ __forceinline__ void operator()(const f32x4 (&acc)[2][2][4][2], const Unit& u, int wr, int wc, int fr_in, int fq_in) const {
;     ...
;         for (int ai = 0; ai < 2; ++ai) {
;             float* hp[4]; f32x4 hv[4][2][2];
; #pragma unroll
;             for (int m = 0; m < 4; ++m) { const int rw = row0 + ai * HALF + m * 16; hp[m] = hrow(LEAD, OUT, rw) + col0;
;                 const float* sp = hp[m];
;                 if (XP) { const int b = rw / LP, sl = rw - b * LP; if (sl >= 128) sp = (b < 2 ? XP + ((size_t)b * SEQ + (sl - 128)) * DM : XS + ((size_t)(b - 2) * SEQ + (sl - 128)) * DM) + col0; }
; #pragma unroll
;                 for (int bj = 0; bj < 2; ++bj) { hv[m][bj][0] = *(const f32x4*)(sp + bj * HALF); hv[m][bj][1] = *(const f32x4*)(sp + bj * HALF + 4); } }
; template <class Epi, class Sched, bool ALIGN_EPI = false, bool SP2 = false>
; __device__ __forceinline__ void gemm_phase(PG8_LAS unsigned char* lds, const Gemm g, const Sched& S, const Epi& E) {
;     ...
;             PG8_LDA(At, 1, 1); PG8_STAGE(PG8_SB(1, 0), b3, voffB); PG8_STAGE(PG8_SB(1, 1), b3 + hstep, voffB); PG8_STAGE(PG8_SA(1, 0), a3, voffA);
;             PG8_WAIT_V(8); PG8_WAIT_L(0); PG8_BAR; PG8_MMA(1, 0, At, B0); PG8_MMA(1, 1, At, B1); PG8_BAR; PG8_SCHED;
	s_add_i32 s22, s77, s38
	v_lshl_add_u64 v[202:203], v[202:203], 0, s[28:29]
	s_mov_b32 m0, s22
	ds_read_b128 v[162:165], v205 offset:49152
	ds_read_b128 v[166:169], v205 offset:50176
	ds_read_b128 v[170:173], v205 offset:51200
	ds_read_b128 v[174:177], v205 offset:52224
	ds_read_b128 v[190:193], v205 offset:53248
	ds_read_b128 v[194:197], v205 offset:54272
	ds_read_b128 v[198:201], v205 offset:55296
	ds_read_b128 v[206:209], v205 offset:56320
	global_load_lds_dwordx4 v[202:203], off
	s_add_i32 m0, s22, 0x2000
	s_add_u32 s22, s26, 0xb0080
	v_lshl_add_u64 v[202:203], v[210:211], 0, s[28:29]
	s_addc_u32 s23, s27, 0
	s_add_i32 s26, s78, s38
	global_load_lds_dwordx4 v[202:203], off
	v_lshl_add_u64 v[202:203], s[22:23], 0, v[180:181]
	s_mov_b32 m0, s26
	s_nop 0
	global_load_lds_dwordx4 v[202:203], off
	v_lshl_add_u64 v[202:203], s[22:23], 0, v[184:185]
	s_add_i32 m0, s26, 0x2000
	s_nop 0
	global_load_lds_dwordx4 v[202:203], off
	v_lshl_add_u64 v[202:203], v[220:221], 0, s[28:29]
	s_mov_b32 m0, s61
	s_nop 0
	global_load_lds_dwordx4 v[202:203], off
	v_lshl_add_u64 v[202:203], v[222:223], 0, s[28:29]
	s_mov_b32 m0, s64
	s_nop 0
	global_load_lds_dwordx4 v[202:203], off
	s_waitcnt vmcnt(8)
	s_waitcnt lgkmcnt(0)
	s_barrier
	s_setprio 1
	s_waitcnt lgkmcnt(0)
	v_mfma_f32_16x16x32_bf16 v[62:65], v[130:133], v[162:165], v[62:65]
	v_mfma_f32_16x16x32_bf16 v[58:61], v[138:141], v[162:165], v[58:61]
	v_mfma_f32_16x16x32_bf16 v[54:57], v[130:133], v[170:173], v[54:57]
	v_mfma_f32_16x16x32_bf16 v[46:49], v[138:141], v[170:173], v[46:49]
	v_mfma_f32_16x16x32_bf16 v[38:41], v[130:133], v[190:193], v[38:41]
	v_mfma_f32_16x16x32_bf16 v[30:33], v[138:141], v[190:193], v[30:33]
	v_mfma_f32_16x16x32_bf16 v[14:17], v[130:133], v[198:201], v[14:17]
	v_mfma_f32_16x16x32_bf16 v[10:13], v[138:141], v[198:201], v[10:13]
	v_mfma_f32_16x16x32_bf16 v[62:65], v[134:137], v[166:169], v[62:65]
	v_mfma_f32_16x16x32_bf16 v[58:61], v[142:145], v[166:169], v[58:61]
	v_mfma_f32_16x16x32_bf16 v[54:57], v[134:137], v[174:177], v[54:57]
	v_mfma_f32_16x16x32_bf16 v[46:49], v[142:145], v[174:177], v[46:49]
	v_mfma_f32_16x16x32_bf16 v[38:41], v[134:137], v[194:197], v[38:41]
	v_mfma_f32_16x16x32_bf16 v[30:33], v[142:145], v[194:197], v[30:33]
	v_mfma_f32_16x16x32_bf16 v[14:17], v[134:137], v[206:209], v[14:17]
	v_mfma_f32_16x16x32_bf16 v[10:13], v[142:145], v[206:209], v[10:13]
	s_setprio 0
	s_setprio 1
	v_mfma_f32_16x16x32_bf16 v[50:53], v[146:149], v[162:165], v[50:53]
	v_mfma_f32_16x16x32_bf16 v[42:45], v[154:157], v[162:165], v[42:45]
	v_mfma_f32_16x16x32_bf16 v[34:37], v[146:149], v[170:173], v[34:37]
	v_mfma_f32_16x16x32_bf16 v[26:29], v[154:157], v[170:173], v[26:29]
	v_mfma_f32_16x16x32_bf16 v[22:25], v[146:149], v[190:193], v[22:25]
	v_mfma_f32_16x16x32_bf16 v[18:21], v[154:157], v[190:193], v[18:21]
	v_mfma_f32_16x16x32_bf16 v[6:9], v[146:149], v[198:201], v[6:9]
	v_mfma_f32_16x16x32_bf16 v[2:5], v[154:157], v[198:201], v[2:5]
	v_mfma_f32_16x16x32_bf16 v[50:53], v[150:153], v[166:169], v[50:53]
	v_mfma_f32_16x16x32_bf16 v[42:45], v[158:161], v[166:169], v[42:45]
	v_mfma_f32_16x16x32_bf16 v[34:37], v[150:153], v[174:177], v[34:37]
	v_mfma_f32_16x16x32_bf16 v[26:29], v[158:161], v[174:177], v[26:29]
	v_mfma_f32_16x16x32_bf16 v[22:25], v[150:153], v[194:197], v[22:25]
	v_mfma_f32_16x16x32_bf16 v[18:21], v[158:161], v[194:197], v[18:21]
	v_mfma_f32_16x16x32_bf16 v[6:9], v[150:153], v[206:209], v[6:9]
	v_mfma_f32_16x16x32_bf16 v[2:5], v[158:161], v[206:209], v[2:5]
	s_setprio 0
	s_barrier
	s_add_i32 s76, s76, 2
	s_add_u32 s74, s74, 0x100
	s_addc_u32 s75, s75, 0
	s_cmp_gt_u32 s76, 41
	s_mov_b64 s[22:23], s[24:25]
	s_cbranch_scc0 .LBB0_388
	s_and_b64 vcc, exec, s[8:9]
	s_cbranch_vccz .LBB0_391
	s_barrier
.LBB0_391:
	s_lshl_b32 s22, s73, 8
	v_mov_b32_e32 v136, v252
	s_add_i32 s22, s22, s53
	s_nop 0
	v_and_or_b32 v206, v136, 15, s22
	v_mul_hi_i32 v0, v206, s33
	v_lshrrev_b32_e32 v130, 31, v0
	v_ashrrev_i32_e32 v0, 12, v0
	v_add_u32_e32 v134, v0, v130
	v_mad_i32_i24 v0, v134, s51, v206
	v_cmp_lt_i32_e32 vcc, s3, v0
	s_and_saveexec_b64 s[22:23], vcc
	s_xor_b64 s[22:23], exec, s[22:23]
	v_ashrrev_i32_e32 v135, 31, v134
	v_add_u32_e32 v0, 0xffffff80, v0
	v_lshlrev_b64 v[130:131], 25, v[134:135]
	v_lshl_add_u64 v[132:133], s[56:57], 0, v[130:131]
	v_mov_b64_e32 v[130:131], v[0:1]
	s_andn2_saveexec_b64 s[22:23], s[22:23]
	v_lshl_add_u32 v130, v134, 7, v0
	v_ashrrev_i32_e32 v131, 31, v130
	v_mov_b64_e32 v[132:133], s[18:19]
	s_or_b64 exec, exec, s[22:23]
	v_lshrrev_b32_e32 v0, 1, v136
	s_lshl_b32 s22, s72, 8
	v_and_or_b32 v0, v0, 24, s22
	v_or_b32_e32 v190, s60, v0
	v_lshlrev_b64 v[130:131], 12, v[130:131]
	v_ashrrev_i32_e32 v191, 31, v190
	v_lshl_add_u64 v[130:131], v[132:133], 0, v[130:131]
	v_lshl_add_u64 v[192:193], v[190:191], 2, v[130:131]
	flat_load_dwordx4 v[150:153], v[192:193]
	flat_load_dwordx4 v[142:145], v[192:193] offset:16
	flat_load_dwordx4 v[134:137], v[192:193] offset:512
	flat_load_dwordx4 v[130:133], v[192:193] offset:528
	v_or_b32_e32 v0, 16, v206
	v_mul_hi_i32 v138, v0, s33
	v_lshrrev_b32_e32 v139, 31, v138
	v_ashrrev_i32_e32 v138, 12, v138
	v_add_u32_e32 v138, v138, v139
	v_mad_i32_i24 v0, v138, s51, v0
	v_cmp_lt_i32_e32 vcc, s3, v0
	s_and_saveexec_b64 s[22:23], vcc
	s_xor_b64 s[22:23], exec, s[22:23]
	v_ashrrev_i32_e32 v139, 31, v138
	v_add_u32_e32 v0, 0xffffff80, v0
	v_lshlrev_b64 v[138:139], 25, v[138:139]
	v_lshl_add_u64 v[146:147], s[56:57], 0, v[138:139]
	v_mov_b64_e32 v[140:141], v[0:1]
	s_andn2_saveexec_b64 s[22:23], s[22:23]
	v_lshl_add_u32 v140, v138, 7, v0
	v_ashrrev_i32_e32 v141, 31, v140
	v_mov_b64_e32 v[146:147], s[18:19]
	s_or_b64 exec, exec, s[22:23]
;     __device__ __forceinline__ void operator()(const f32x4 (&acc)[2][2][4][2], const Unit& u, int wr, int wc, int fr_in, int fq_in) const {
;     ...
;         for (int ai = 0; ai < 2; ++ai) {
;             float* hp[4]; f32x4 hv[4][2][2];
; #pragma unroll
;             for (int m = 0; m < 4; ++m) { const int rw = row0 + ai * HALF + m * 16; hp[m] = hrow(LEAD, OUT, rw) + col0;
;                 const float* sp = hp[m];
;                 if (XP) { const int b = rw / LP, sl = rw - b * LP; if (sl >= 128) sp = (b < 2 ? XP + ((size_t)b * SEQ + (sl - 128)) * DM : XS + ((size_t)(b - 2) * SEQ + (sl - 128)) * DM) + col0; }
; #pragma unroll
;                 for (int bj = 0; bj < 2; ++bj) { hv[m][bj][0] = *(const f32x4*)(sp + bj * HALF); hv[m][bj][1] = *(const f32x4*)(sp + bj * HALF + 4); } }
; #pragma unroll
;             for (int m = 0; m < 4; ++m) {
;                 const int row = row0 + ai * HALF + m * 16;
;                 bf16_t* xp = XN + (size_t)row * DM + col0;
;                 float sq = 0.f;
; #pragma unroll
;                 for (int bj = 0; bj < 2; ++bj) {
;                     const f32x4 a = hv[m][bj][0] + acc[ai][bj][m][0] * alpha, b = hv[m][bj][1] + acc[ai][bj][m][1] * alpha;
;                     *(f32x4*)(hp[m] + bj * HALF) = a; *(f32x4*)(hp[m] + bj * HALF + 4) = b;
;                     sq += (a[0] * a[0] + a[1] * a[1]) + (a[2] * a[2] + a[3] * a[3]) + (b[0] * b[0] + b[1] * b[1]) + (b[2] * b[2] + b[3] * b[3]);
;                 }
	v_lshlrev_b64 v[138:139], 12, v[140:141]
	v_lshl_add_u64 v[138:139], v[146:147], 0, v[138:139]
	v_lshl_add_u64 v[194:195], v[190:191], 2, v[138:139]
	flat_load_dwordx4 v[166:169], v[194:195]
	flat_load_dwordx4 v[158:161], v[194:195] offset:16
	flat_load_dwordx4 v[146:149], v[194:195] offset:512
	flat_load_dwordx4 v[138:141], v[194:195] offset:528
	v_or_b32_e32 v0, 32, v206
	v_mul_hi_i32 v154, v0, s33
	v_lshrrev_b32_e32 v155, 31, v154
	v_ashrrev_i32_e32 v154, 12, v154
	v_add_u32_e32 v154, v154, v155
	v_mad_i32_i24 v0, v154, s51, v0
	v_cmp_lt_i32_e32 vcc, s3, v0
	s_and_saveexec_b64 s[22:23], vcc
	s_xor_b64 s[22:23], exec, s[22:23]
	v_ashrrev_i32_e32 v155, 31, v154
	v_add_u32_e32 v0, 0xffffff80, v0
	v_lshlrev_b64 v[154:155], 25, v[154:155]
	v_lshl_add_u64 v[162:163], s[56:57], 0, v[154:155]
	v_mov_b64_e32 v[156:157], v[0:1]
	s_andn2_saveexec_b64 s[22:23], s[22:23]
	v_lshl_add_u32 v156, v154, 7, v0
	v_ashrrev_i32_e32 v157, 31, v156
	v_mov_b64_e32 v[162:163], s[18:19]
	s_or_b64 exec, exec, s[22:23]
	v_lshlrev_b64 v[154:155], 12, v[156:157]
	v_lshl_add_u64 v[154:155], v[162:163], 0, v[154:155]
	v_lshl_add_u64 v[196:197], v[190:191], 2, v[154:155]
	flat_load_dwordx4 v[174:177], v[196:197]
	flat_load_dwordx4 v[170:173], v[196:197] offset:16
	flat_load_dwordx4 v[162:165], v[196:197] offset:512
	flat_load_dwordx4 v[154:157], v[196:197] offset:528
	v_or_b32_e32 v0, 48, v206
	v_mul_hi_i32 v198, v0, s33
	v_lshrrev_b32_e32 v199, 31, v198
	v_ashrrev_i32_e32 v198, 12, v198
	v_add_u32_e32 v198, v198, v199
	v_mad_i32_i24 v0, v198, s51, v0
	v_cmp_lt_i32_e32 vcc, s3, v0
	s_and_saveexec_b64 s[22:23], vcc
	s_xor_b64 s[22:23], exec, s[22:23]
	v_ashrrev_i32_e32 v199, 31, v198
	v_add_u32_e32 v0, 0xffffff80, v0
	v_lshlrev_b64 v[198:199], 25, v[198:199]
	v_lshl_add_u64 v[202:203], s[56:57], 0, v[198:199]
	v_mov_b64_e32 v[200:201], v[0:1]
	s_andn2_saveexec_b64 s[22:23], s[22:23]
	v_lshl_add_u32 v200, v198, 7, v0
	v_ashrrev_i32_e32 v201, 31, v200
	v_mov_b64_e32 v[202:203], s[18:19]
	s_or_b64 exec, exec, s[22:23]
	v_lshlrev_b64 v[198:199], 12, v[200:201]
	v_lshl_add_u64 v[198:199], v[202:203], 0, v[198:199]
	v_lshl_add_u64 v[202:203], v[190:191], 2, v[198:199]
	flat_load_dwordx4 v[198:201], v[202:203]
	flat_load_dwordx4 v[208:211], v[202:203] offset:16
	flat_load_dwordx4 v[220:223], v[202:203] offset:512
	flat_load_dwordx4 v[224:227], v[202:203] offset:528
	v_add_u32_e32 v0, 0x80, v206
	s_waitcnt vmcnt(0) lgkmcnt(0)
	v_pk_fma_f32 v[106:107], v[106:107], 0.5, v[130:131] op_sel_hi:[1,0,1]
	v_mul_hi_i32 v130, v0, s33
	v_pk_fma_f32 v[128:129], v[128:129], 0.5, v[152:153] op_sel_hi:[1,0,1]
	v_pk_fma_f32 v[126:127], v[126:127], 0.5, v[150:151] op_sel_hi:[1,0,1]
	v_pk_fma_f32 v[82:83], v[82:83], 0.5, v[154:155] op_sel_hi:[1,0,1]
	v_lshrrev_b32_e32 v131, 31, v130
	v_ashrrev_i32_e32 v130, 12, v130
	v_pk_fma_f32 v[124:125], v[124:125], 0.5, v[144:145] op_sel_hi:[1,0,1]
	v_pk_fma_f32 v[122:123], v[122:123], 0.5, v[142:143] op_sel_hi:[1,0,1]
	v_pk_fma_f32 v[116:117], v[116:117], 0.5, v[136:137] op_sel_hi:[1,0,1]
	v_pk_fma_f32 v[114:115], v[114:115], 0.5, v[134:135] op_sel_hi:[1,0,1]
	v_pk_fma_f32 v[108:109], v[108:109], 0.5, v[132:133] op_sel_hi:[1,0,1]
	v_pk_fma_f32 v[120:121], v[120:121], 0.5, v[168:169] op_sel_hi:[1,0,1]
	v_pk_fma_f32 v[118:119], v[118:119], 0.5, v[166:167] op_sel_hi:[1,0,1]
	v_pk_fma_f32 v[112:113], v[112:113], 0.5, v[160:161] op_sel_hi:[1,0,1]
	v_pk_fma_f32 v[110:111], v[110:111], 0.5, v[158:159] op_sel_hi:[1,0,1]
	v_pk_fma_f32 v[100:101], v[100:101], 0.5, v[148:149] op_sel_hi:[1,0,1]
	v_pk_fma_f32 v[98:99], v[98:99], 0.5, v[146:147] op_sel_hi:[1,0,1]
	v_pk_fma_f32 v[92:93], v[92:93], 0.5, v[140:141] op_sel_hi:[1,0,1]
	v_pk_fma_f32 v[90:91], v[90:91], 0.5, v[138:139] op_sel_hi:[1,0,1]
	v_pk_fma_f32 v[104:105], v[104:105], 0.5, v[176:177] op_sel_hi:[1,0,1]
	v_pk_fma_f32 v[102:103], v[102:103], 0.5, v[174:175] op_sel_hi:[1,0,1]
	v_pk_fma_f32 v[96:97], v[96:97], 0.5, v[172:173] op_sel_hi:[1,0,1]
	v_pk_fma_f32 v[94:95], v[94:95], 0.5, v[170:171] op_sel_hi:[1,0,1]
	v_pk_fma_f32 v[88:89], v[88:89], 0.5, v[164:165] op_sel_hi:[1,0,1]
	v_pk_fma_f32 v[86:87], v[86:87], 0.5, v[162:163] op_sel_hi:[1,0,1]
	v_pk_fma_f32 v[84:85], v[84:85], 0.5, v[156:157] op_sel_hi:[1,0,1]
	flat_store_dwordx4 v[192:193], v[126:129]
	flat_store_dwordx4 v[192:193], v[122:125] offset:16
	flat_store_dwordx4 v[192:193], v[114:117] offset:512
	flat_store_dwordx4 v[192:193], v[106:109] offset:528
	flat_store_dwordx4 v[194:195], v[118:121]
	flat_store_dwordx4 v[194:195], v[110:113] offset:16
	flat_store_dwordx4 v[194:195], v[98:101] offset:512
	flat_store_dwordx4 v[194:195], v[90:93] offset:528
	flat_store_dwordx4 v[196:197], v[102:105]
	flat_store_dwordx4 v[196:197], v[94:97] offset:16
	flat_store_dwordx4 v[196:197], v[86:89] offset:512
	flat_store_dwordx4 v[196:197], v[82:85] offset:528
	v_pk_fma_f32 v[80:81], v[80:81], 0.5, v[200:201] op_sel_hi:[1,0,1]
	s_nop 0
	v_add_u32_e32 v82, v130, v131
	v_mad_i32_i24 v0, v82, s51, v0
	v_pk_fma_f32 v[78:79], v[78:79], 0.5, v[198:199] op_sel_hi:[1,0,1]
	v_pk_fma_f32 v[68:69], v[68:69], 0.5, v[226:227] op_sel_hi:[1,0,1]
	v_pk_fma_f32 v[66:67], v[66:67], 0.5, v[224:225] op_sel_hi:[1,0,1]
	v_cmp_lt_i32_e32 vcc, s3, v0
	v_pk_fma_f32 v[76:77], v[76:77], 0.5, v[210:211] op_sel_hi:[1,0,1]
	v_pk_fma_f32 v[74:75], v[74:75], 0.5, v[208:209] op_sel_hi:[1,0,1]
	v_pk_fma_f32 v[72:73], v[72:73], 0.5, v[222:223] op_sel_hi:[1,0,1]
	v_pk_fma_f32 v[70:71], v[70:71], 0.5, v[220:221] op_sel_hi:[1,0,1]
	flat_store_dwordx4 v[202:203], v[78:81]
	flat_store_dwordx4 v[202:203], v[74:77] offset:16
	flat_store_dwordx4 v[202:203], v[70:73] offset:512
	flat_store_dwordx4 v[202:203], v[66:69] offset:528
; #define PG8_BAR __builtin_amdgcn_s_barrier()
;     __device__ __forceinline__ void operator()(const f32x4 (&acc)[2][2][4][2], const Unit& u, int wr, int wc, int fr_in, int fq_in) const {
;     ...
;             for (int m = 0; m < 4; ++m) { const int rw = row0 + ai * HALF + m * 16; hp[m] = hrow(LEAD, OUT, rw) + col0;
;                 const float* sp = hp[m];
;                 if (XP) { const int b = rw / LP, sl = rw - b * LP; if (sl >= 128) sp = (b < 2 ? XP + ((size_t)b * SEQ + (sl - 128)) * DM : XS + ((size_t)(b - 2) * SEQ + (sl - 128)) * DM) + col0; }
; #pragma unroll
;                 for (int bj = 0; bj < 2; ++bj) { hv[m][bj][0] = *(const f32x4*)(sp + bj * HALF); hv[m][bj][1] = *(const f32x4*)(sp + bj * HALF + 4); } }
; #pragma unroll
;             for (int m = 0; m < 4; ++m) {
;                 const int row = row0 + ai * HALF + m * 16;
;                 bf16_t* xp = XN + (size_t)row * DM + col0;
;                 float sq = 0.f;
; #pragma unroll
;                 for (int bj = 0; bj < 2; ++bj) {
;                     const f32x4 a = hv[m][bj][0] + acc[ai][bj][m][0] * alpha, b = hv[m][bj][1] + acc[ai][bj][m][1] * alpha;
;                     *(f32x4*)(hp[m] + bj * HALF) = a; *(f32x4*)(hp[m] + bj * HALF + 4) = b;
;                     sq += (a[0] * a[0] + a[1] * a[1]) + (a[2] * a[2] + a[3] * a[3]) + (b[0] * b[0] + b[1] * b[1]) + (b[2] * b[2] + b[3] * b[3]);
;                 }
; template <class Epi, class Sched, bool ALIGN_EPI = false, bool SP2 = false>
; __device__ __forceinline__ void gemm_phase(PG8_LAS unsigned char* lds, const Gemm g, const Sched& S, const Epi& E) {
;     ...
;         if constexpr (!Epi::AFTER_DRAIN) { E(acc, cur, wr, wc, fr, fq); S.done(cur); }
;         if (!has_next) break;
; #pragma unroll
;         for (int a = 0; a < 2; ++a)
; #pragma unroll
;             for (int b = 0; b < 2; ++b)
; #pragma unroll
;                 for (int m = 0; m < 4; ++m)
; #pragma unroll
;                     for (int n = 0; n < 2; ++n) acc[a][b][m][n] = (f32x4){0.f, 0.f, 0.f, 0.f};
;         cur = nxt; cA = nA; cB = nB; ++ui;
;         if constexpr (ALIGN_EPI) { if (wr == 1) PG8_BAR; }
;     }
	s_and_saveexec_b64 s[22:23], vcc
	s_xor_b64 s[22:23], exec, s[22:23]
	v_mul_i32_i24_e32 v0, 0xffffdf80, v82
	v_ashrrev_i32_e32 v83, 31, v82
	v_add_u32_e32 v0, v0, v206
	v_lshlrev_b64 v[66:67], 25, v[82:83]
	v_lshl_add_u64 v[68:69], s[56:57], 0, v[66:67]
	v_mov_b64_e32 v[66:67], v[0:1]
	s_andn2_saveexec_b64 s[22:23], s[22:23]
	v_lshl_add_u32 v66, v82, 7, v0
	v_ashrrev_i32_e32 v67, 31, v66
	v_mov_b64_e32 v[68:69], s[18:19]
	s_or_b64 exec, exec, s[22:23]
	v_lshlrev_b64 v[66:67], 12, v[66:67]
	v_lshl_add_u64 v[66:67], v[68:69], 0, v[66:67]
	v_lshl_add_u64 v[114:115], v[190:191], 2, v[66:67]
	flat_load_dwordx4 v[86:89], v[114:115]
	flat_load_dwordx4 v[78:81], v[114:115] offset:16
	flat_load_dwordx4 v[70:73], v[114:115] offset:512
	flat_load_dwordx4 v[66:69], v[114:115] offset:528
	v_add_u32_e32 v0, 0x90, v206
	v_mul_hi_i32 v74, v0, s33
	v_lshrrev_b32_e32 v75, 31, v74
	v_ashrrev_i32_e32 v74, 12, v74
	v_add_u32_e32 v74, v74, v75
	v_mad_i32_i24 v0, v74, s51, v0
	v_cmp_lt_i32_e32 vcc, s3, v0
	s_and_saveexec_b64 s[22:23], vcc
	s_xor_b64 s[22:23], exec, s[22:23]
	v_ashrrev_i32_e32 v75, 31, v74
	v_add_u32_e32 v0, 0xffffff80, v0
	v_lshlrev_b64 v[74:75], 25, v[74:75]
	v_lshl_add_u64 v[82:83], s[56:57], 0, v[74:75]
	v_mov_b64_e32 v[76:77], v[0:1]
	s_andn2_saveexec_b64 s[22:23], s[22:23]
	v_lshl_add_u32 v76, v74, 7, v0
	v_ashrrev_i32_e32 v77, 31, v76
	v_mov_b64_e32 v[82:83], s[18:19]
	s_or_b64 exec, exec, s[22:23]
	v_lshlrev_b64 v[74:75], 12, v[76:77]
	v_lshl_add_u64 v[74:75], v[82:83], 0, v[74:75]
	v_lshl_add_u64 v[116:117], v[190:191], 2, v[74:75]
	flat_load_dwordx4 v[102:105], v[116:117]
	flat_load_dwordx4 v[94:97], v[116:117] offset:16
	flat_load_dwordx4 v[82:85], v[116:117] offset:512
	flat_load_dwordx4 v[74:77], v[116:117] offset:528
	v_add_u32_e32 v0, 0xa0, v206
	v_mul_hi_i32 v90, v0, s33
	v_lshrrev_b32_e32 v91, 31, v90
	v_ashrrev_i32_e32 v90, 12, v90
	v_add_u32_e32 v90, v90, v91
	v_mad_i32_i24 v0, v90, s51, v0
	v_cmp_lt_i32_e32 vcc, s3, v0
	s_and_saveexec_b64 s[22:23], vcc
	s_xor_b64 s[22:23], exec, s[22:23]
	v_ashrrev_i32_e32 v91, 31, v90
	v_add_u32_e32 v0, 0xffffff80, v0
	v_lshlrev_b64 v[90:91], 25, v[90:91]
	v_lshl_add_u64 v[98:99], s[56:57], 0, v[90:91]
	v_mov_b64_e32 v[92:93], v[0:1]
	s_andn2_saveexec_b64 s[22:23], s[22:23]
	v_lshl_add_u32 v92, v90, 7, v0
	v_ashrrev_i32_e32 v93, 31, v92
	v_mov_b64_e32 v[98:99], s[18:19]
	s_or_b64 exec, exec, s[22:23]
	v_lshlrev_b64 v[90:91], 12, v[92:93]
	v_lshl_add_u64 v[90:91], v[98:99], 0, v[90:91]
	v_lshl_add_u64 v[118:119], v[190:191], 2, v[90:91]
	flat_load_dwordx4 v[110:113], v[118:119]
	flat_load_dwordx4 v[106:109], v[118:119] offset:16
	flat_load_dwordx4 v[98:101], v[118:119] offset:512
	flat_load_dwordx4 v[90:93], v[118:119] offset:528
	v_add_u32_e32 v0, 0xb0, v206
	v_mul_hi_i32 v120, v0, s33
	v_lshrrev_b32_e32 v121, 31, v120
	v_ashrrev_i32_e32 v120, 12, v120
	v_add_u32_e32 v120, v120, v121
	v_mad_i32_i24 v0, v120, s51, v0
	v_cmp_lt_i32_e32 vcc, s3, v0
	s_and_saveexec_b64 s[22:23], vcc
	s_xor_b64 s[22:23], exec, s[22:23]
	v_ashrrev_i32_e32 v121, 31, v120
	v_add_u32_e32 v0, 0xffffff80, v0
	v_lshlrev_b64 v[120:121], 25, v[120:121]
	v_lshl_add_u64 v[124:125], s[56:57], 0, v[120:121]
	v_mov_b64_e32 v[122:123], v[0:1]
	s_andn2_saveexec_b64 s[22:23], s[22:23]
	v_lshl_add_u32 v122, v120, 7, v0
	v_ashrrev_i32_e32 v123, 31, v122
	v_mov_b64_e32 v[124:125], s[18:19]
	s_or_b64 exec, exec, s[22:23]
	v_lshlrev_b64 v[120:121], 12, v[122:123]
	v_lshl_add_u64 v[120:121], v[124:125], 0, v[120:121]
	v_lshl_add_u64 v[136:137], v[190:191], 2, v[120:121]
	flat_load_dwordx4 v[120:123], v[136:137]
	flat_load_dwordx4 v[124:127], v[136:137] offset:16
	flat_load_dwordx4 v[128:131], v[136:137] offset:512
	flat_load_dwordx4 v[132:135], v[136:137] offset:528
	s_waitcnt vmcnt(0) lgkmcnt(0)
	v_pk_fma_f32 v[64:65], v[64:65], 0.5, v[88:89] op_sel_hi:[1,0,1]
	v_pk_fma_f32 v[62:63], v[62:63], 0.5, v[86:87] op_sel_hi:[1,0,1]
	s_and_b64 vcc, exec, s[0:1]
	s_mov_b64 s[0:1], -1
	v_pk_fma_f32 v[60:61], v[60:61], 0.5, v[80:81] op_sel_hi:[1,0,1]
	v_pk_fma_f32 v[58:59], v[58:59], 0.5, v[78:79] op_sel_hi:[1,0,1]
	v_pk_fma_f32 v[52:53], v[52:53], 0.5, v[72:73] op_sel_hi:[1,0,1]
	v_pk_fma_f32 v[50:51], v[50:51], 0.5, v[70:71] op_sel_hi:[1,0,1]
	v_pk_fma_f32 v[44:45], v[44:45], 0.5, v[68:69] op_sel_hi:[1,0,1]
	v_pk_fma_f32 v[42:43], v[42:43], 0.5, v[66:67] op_sel_hi:[1,0,1]
	v_pk_fma_f32 v[56:57], v[56:57], 0.5, v[104:105] op_sel_hi:[1,0,1]
	v_pk_fma_f32 v[54:55], v[54:55], 0.5, v[102:103] op_sel_hi:[1,0,1]
	v_pk_fma_f32 v[48:49], v[48:49], 0.5, v[96:97] op_sel_hi:[1,0,1]
	v_pk_fma_f32 v[46:47], v[46:47], 0.5, v[94:95] op_sel_hi:[1,0,1]
	v_pk_fma_f32 v[36:37], v[36:37], 0.5, v[84:85] op_sel_hi:[1,0,1]
	v_pk_fma_f32 v[34:35], v[34:35], 0.5, v[82:83] op_sel_hi:[1,0,1]
	v_pk_fma_f32 v[28:29], v[28:29], 0.5, v[76:77] op_sel_hi:[1,0,1]
	v_pk_fma_f32 v[26:27], v[26:27], 0.5, v[74:75] op_sel_hi:[1,0,1]
	v_pk_fma_f32 v[40:41], v[40:41], 0.5, v[112:113] op_sel_hi:[1,0,1]
	v_pk_fma_f32 v[38:39], v[38:39], 0.5, v[110:111] op_sel_hi:[1,0,1]
	v_pk_fma_f32 v[32:33], v[32:33], 0.5, v[108:109] op_sel_hi:[1,0,1]
	v_pk_fma_f32 v[30:31], v[30:31], 0.5, v[106:107] op_sel_hi:[1,0,1]
	v_pk_fma_f32 v[24:25], v[24:25], 0.5, v[100:101] op_sel_hi:[1,0,1]
	v_pk_fma_f32 v[22:23], v[22:23], 0.5, v[98:99] op_sel_hi:[1,0,1]
	v_pk_fma_f32 v[20:21], v[20:21], 0.5, v[92:93] op_sel_hi:[1,0,1]
	v_pk_fma_f32 v[18:19], v[18:19], 0.5, v[90:91] op_sel_hi:[1,0,1]
	flat_store_dwordx4 v[114:115], v[62:65]
	flat_store_dwordx4 v[114:115], v[58:61] offset:16
	flat_store_dwordx4 v[114:115], v[50:53] offset:512
	flat_store_dwordx4 v[114:115], v[42:45] offset:528
	flat_store_dwordx4 v[116:117], v[54:57]
	flat_store_dwordx4 v[116:117], v[46:49] offset:16
	flat_store_dwordx4 v[116:117], v[34:37] offset:512
	flat_store_dwordx4 v[116:117], v[26:29] offset:528
	flat_store_dwordx4 v[118:119], v[38:41]
	flat_store_dwordx4 v[118:119], v[30:33] offset:16
	flat_store_dwordx4 v[118:119], v[22:25] offset:512
	flat_store_dwordx4 v[118:119], v[18:21] offset:528
	v_pk_fma_f32 v[16:17], v[16:17], 0.5, v[122:123] op_sel_hi:[1,0,1]
	v_pk_fma_f32 v[14:15], v[14:15], 0.5, v[120:121] op_sel_hi:[1,0,1]
	v_pk_fma_f32 v[12:13], v[12:13], 0.5, v[126:127] op_sel_hi:[1,0,1]
	v_pk_fma_f32 v[10:11], v[10:11], 0.5, v[124:125] op_sel_hi:[1,0,1]
	v_pk_fma_f32 v[8:9], v[8:9], 0.5, v[130:131] op_sel_hi:[1,0,1]
	v_pk_fma_f32 v[6:7], v[6:7], 0.5, v[128:129] op_sel_hi:[1,0,1]
	v_pk_fma_f32 v[4:5], v[4:5], 0.5, v[134:135] op_sel_hi:[1,0,1]
	v_pk_fma_f32 v[2:3], v[2:3], 0.5, v[132:133] op_sel_hi:[1,0,1]
	flat_store_dwordx4 v[136:137], v[14:17]
	flat_store_dwordx4 v[136:137], v[10:13] offset:16
	flat_store_dwordx4 v[136:137], v[6:9] offset:512
	flat_store_dwordx4 v[136:137], v[2:5] offset:528
	s_mov_b32 s98, 1
	s_cbranch_vccnz .LBB0_376
	s_andn2_b64 vcc, exec, s[6:7]
	s_cbranch_vccnz .LBB0_375
	s_barrier
	s_branch .LBB0_375

; #define PG8_STAGE(bufoff, gbase, voff) do { _Pragma("unroll") for (int _i = 0; _i < 2; ++_i) \
;         __builtin_amdgcn_global_load_lds((const unsigned*)((const char*)(gbase) + (voff)[_i]), (PG8_LAS unsigned*)(lds + (bufoff) + ldsw + _i * 8192), 16, 0, 0); } while (0)
; #define PG8_WAIT_V(n) asm volatile("s_waitcnt vmcnt(" #n ")" ::: "memory")
; #define PG8_BAR __builtin_amdgcn_s_barrier()
; template <class Epi, class Sched, bool ALIGN_EPI = false, bool SP2 = false>
; __device__ __forceinline__ void gemm_phase(PG8_LAS unsigned char* lds, const Gemm g, const Sched& S, const Epi& E) {
;     ...
;     for (int i = 0; i < 2; ++i) { int R, C; stage_rc(tid * 16 + i * 8192, R, C); const int Rb = Epi::PERM ? ((R & ~31) + perm32(R & 31)) : R;
;         voffA[i] = (unsigned)(R * K + C) * 2u; voffB[i] = (unsigned)(Rb * K + C) * 2u; }
;     const size_t kstep = (size_t)(BK * 2);
;     const size_t hstep = (size_t)HALF * K * 2;
;     const size_t tstep = 2 * hstep;
;     const unsigned ldsw = (unsigned)wid * 1024u;
;     const int aoff = lds_byte(wr * 64 + fr, fq * 8), boff = lds_byte(wc * 32 + fr, fq * 8);
;     ...
;     Unit cur, nxt; int ui = 0;
;     if (!S.next(0, cur)) return;
;     f32x4 acc[2][2][4][2];
; #pragma unroll
;     for (int a = 0; a < 2; ++a)
; #pragma unroll
;         for (int b = 0; b < 2; ++b)
; #pragma unroll
;             for (int m = 0; m < 4; ++m)
; #pragma unroll
;                 for (int n = 0; n < 2; ++n) acc[a][b][m][n] = (f32x4){0.f, 0.f, 0.f, 0.f};
;     bf16x8 At[4][2], B0[2][2], B1[2][2];
;     const char* cA = (const char*)g.A + (size_t)cur.pm * tstep; const char* cB = (const char*)g.Bt + (size_t)cur.pn * tstep;
;     S.a_ready(cur);
;     if constexpr (SP2) {
;         PG8_STAGE(PG8_SB(0, 0), cB, voffB); PG8_STAGE(PG8_SB(0, 1), cB + hstep, voffB); PG8_STAGE(PG8_SA(0, 0), cA, voffA); PG8_STAGE(PG8_SA(0, 1), cA + hstep, voffA);
;         if (wr == 1) PG8_BAR;
;         PG8_WAIT_V(2); PG8_BAR;
;         PG8_STAGE(PG8_SB(1, 0), cB + kstep, voffB); PG8_STAGE(PG8_SA(1, 0), cA + kstep, voffA); PG8_STAGE(PG8_SB(1, 1), cB + hstep + kstep, voffB);
;         PG8_WAIT_V(6); PG8_BAR;
.LBB0_1069:
	v_readlane_b32 s8, v254, 55
	v_readlane_b32 s9, v254, 56
	v_readlane_b32 s68, v254, 17
	s_lshl_b64 s[8:9], s[8:9], 12
	v_readlane_b32 s76, v254, 25
	v_readlane_b32 s77, v254, 26
	s_add_u32 s8, s76, s8
	s_addc_u32 s9, s77, s9
	s_lshl_b32 s0, s0, 5
	v_readlane_b32 s69, v254, 18
	s_and_b32 s64, s0, 0x60
	s_add_i32 m0, s27, 0x18000
	v_lshl_add_u64 v[8:9], v[8:9], 0, s[28:29]
	s_lshl_b32 s63, s1, 6
	s_lshl_b32 s5, s1, 13
	s_lshl_b32 s15, s64, 7
	s_waitcnt vmcnt(2)
	s_barrier
	global_load_lds_dwordx4 v[8:9], off
	v_lshl_add_u64 v[6:7], v[6:7], 0, s[28:29]
	s_add_i32 m0, s27, 0x1a000
	s_add_i32 s65, s27, 0x8000
	s_add_i32 s69, s27, 0xa000
	global_load_lds_dwordx4 v[6:7], off
	v_lshl_add_u64 v[2:3], v[2:3], 0, s[28:29]
	s_mov_b32 m0, s65
	s_add_u32 s0, s36, 0x40080
	global_load_lds_dwordx4 v[2:3], off
	v_lshl_add_u64 v[2:3], v[4:5], 0, s[28:29]
	s_mov_b32 m0, s69
	s_addc_u32 s1, s37, 0
	global_load_lds_dwordx4 v[2:3], off
	s_add_i32 m0, s27, 0x1c000
	v_lshl_add_u64 v[2:3], s[0:1], 0, v[222:223]
	global_load_lds_dwordx4 v[2:3], off
	v_lshl_add_u64 v[2:3], s[0:1], 0, v[226:227]
	s_add_i32 m0, s27, 0x1e000
	s_movk_i32 s0, 0x3c0
	global_load_lds_dwordx4 v[2:3], off
	v_and_b32_e32 v2, 48, v0
	v_lshlrev_b32_e32 v3, 6, v0
	v_lshlrev_b32_e32 v0, 2, v0
	v_and_or_b32 v2, v3, s0, v2
	v_and_b32_e32 v0, 32, v0
	v_bitop3_b32 v3, v2, s5, v0 bitop3:0xde
	v_bitop3_b32 v210, s15, v2, v0 bitop3:0xf6
	v_lshlrev_b32_e32 v0, 14, v13
	v_and_b32_e32 v0, 0xffff8000, v0
	v_lshl_add_u32 v0, v14, 11, v0
	v_and_b32_e32 v2, 1, v13
	v_lshl_or_b32 v0, v2, 6, v0
	v_lshl_add_u32 v228, v15, 1, v0
	v_lshlrev_b32_e32 v0, 14, v10
	v_and_b32_e32 v0, 0xffff8000, v0
	s_waitcnt vmcnt(6)
	v_lshl_add_u32 v0, v11, 11, v0
	v_and_b32_e32 v2, 1, v10
	v_readlane_b32 s70, v254, 19
	s_cmpk_lt_u32 s14, 0x100
	v_lshl_or_b32 v0, v2, 6, v0
	s_cselect_b64 s[14:15], -1, 0
	v_mov_b32_e32 v229, v1
	v_lshl_add_u32 v230, v12, 1, v0
	v_mov_b32_e32 v231, v1
	s_mov_b32 s70, 0
	v_add_u32_e32 v211, 0, v3
	v_readlane_b32 s71, v254, 20
	v_readlane_b32 s72, v254, 21
	v_readlane_b32 s73, v254, 22
	v_readlane_b32 s74, v254, 23
	v_readlane_b32 s75, v254, 24
	v_readlane_b32 s78, v254, 27
	v_readlane_b32 s79, v254, 28
	v_readlane_b32 s80, v254, 29
	v_readlane_b32 s81, v254, 30
	v_readlane_b32 s82, v254, 31
	v_readlane_b32 s83, v254, 32
	s_barrier
	s_mov_b32 s98, 0
	s_branch .LBB0_1072

; #define PG8_STAGE(bufoff, gbase, voff) do { _Pragma("unroll") for (int _i = 0; _i < 2; ++_i) \
;         __builtin_amdgcn_global_load_lds((const unsigned*)((const char*)(gbase) + (voff)[_i]), (PG8_LAS unsigned*)(lds + (bufoff) + ldsw + _i * 8192), 16, 0, 0); } while (0)
; #define PG8_LDA(dst, b, h) do { _Pragma("unroll") for (int m = 0; m < 4; ++m) _Pragma("unroll") for (int k = 0; k < 2; ++k) dst[m][k] = *(const PG8_LAS bf16x8*)(lds + PG8_SA(b, h) + aoff + m * 2048 + k * 1024); } while (0)
; #define PG8_LDB(dst, b, h) do { _Pragma("unroll") for (int n = 0; n < 2; ++n) _Pragma("unroll") for (int k = 0; k < 2; ++k) dst[n][k] = *(const PG8_LAS bf16x8*)(lds + PG8_SB(b, h) + boff + n * 2048 + k * 1024); } while (0)
; #define PG8_MMA(ai, bj, At, Bt) do { __builtin_amdgcn_s_setprio(1); _Pragma("unroll") for (int m = 0; m < 4; ++m) _Pragma("unroll") for (int n = 0; n < 2; ++n) _Pragma("unroll") for (int k = 0; k < 2; ++k) \
;         acc[ai][bj][m][n] = __builtin_amdgcn_mfma_f32_16x16x32_bf16(Bt[n][k], At[m][k], acc[ai][bj][m][n], 0, 0, 0); __builtin_amdgcn_s_setprio(0); } while (0)
; #define PG8_WAIT_V(n) asm volatile("s_waitcnt vmcnt(" #n ")" ::: "memory")
; #define PG8_WAIT_L(n) asm volatile("s_waitcnt lgkmcnt(" #n ")" ::: "memory")
; #define PG8_BAR __builtin_amdgcn_s_barrier()
; #define PG8_SCHED __builtin_amdgcn_sched_barrier(0)
; template <class Epi, class Sched, bool ALIGN_EPI = false, bool SP2 = false>
; __device__ __forceinline__ void gemm_phase(PG8_LAS unsigned char* lds, const Gemm g, const Sched& S, const Epi& E) {
;     ...
;             PG8_LDB(B0, 0, 0); PG8_LDB(B1, 0, 1); PG8_SCHED; PG8_LDA(At, 0, 0); PG8_STAGE(PG8_SA(1, 1), a1 + hstep, voffA);
;             PG8_WAIT_V(8); PG8_WAIT_L(0); PG8_BAR; PG8_MMA(0, 0, At, B0); PG8_MMA(0, 1, At, B1); PG8_BAR; PG8_SCHED;
;             PG8_LDA(At, 0, 1); PG8_STAGE(PG8_SB(0, 0), b2, voffB); PG8_STAGE(PG8_SB(0, 1), b2 + hstep, voffB); PG8_STAGE(PG8_SA(0, 0), a2, voffA);
;             PG8_WAIT_V(8); PG8_WAIT_L(0); PG8_BAR; PG8_MMA(1, 0, At, B0); PG8_MMA(1, 1, At, B1); PG8_BAR; PG8_SCHED;
.LBB0_1079:
	s_add_u32 s36, s52, 0xfffc0080
	s_addc_u32 s37, s53, -1
	s_add_i32 s75, 0, 0x10000
	s_cmp_eq_u32 s74, 12
	s_cselect_b32 s39, s5, s37
	s_cselect_b32 s38, s21, s36
	v_add_u32_e32 v0, s75, v210
	s_cselect_b32 s37, s17, s73
	s_cselect_b32 s36, s71, s72
	s_add_i32 s78, 0, 0x14000
	ds_read_b128 v[66:69], v0
	ds_read_b128 v[70:73], v0 offset:1024
	ds_read_b128 v[74:77], v0 offset:2048
	ds_read_b128 v[78:81], v0 offset:3072
	v_add_u32_e32 v0, s78, v210
	ds_read_b128 v[146:149], v0
	ds_read_b128 v[150:153], v0 offset:1024
	ds_read_b128 v[154:157], v0 offset:2048
	ds_read_b128 v[158:161], v0 offset:3072
	v_lshl_add_u64 v[194:195], s[52:53], 0, v[230:231]
	s_add_i32 m0, s27, 0xc000
	ds_read_b128 v[162:165], v211
	ds_read_b128 v[166:169], v211 offset:1024
	ds_read_b128 v[170:173], v211 offset:2048
	ds_read_b128 v[174:177], v211 offset:3072
	ds_read_b128 v[178:181], v211 offset:4096
	ds_read_b128 v[182:185], v211 offset:5120
	ds_read_b128 v[186:189], v211 offset:6144
	ds_read_b128 v[190:193], v211 offset:7168
	global_load_lds_dwordx4 v[194:195], off
	v_lshl_add_u64 v[194:195], s[52:53], 0, v[228:229]
	s_add_i32 m0, s27, 0xe000
	s_nop 0
	global_load_lds_dwordx4 v[194:195], off
	s_cmp_lg_u32 s98, 0
	s_cbranch_scc1 .Lrw_out_1
	s_waitcnt vmcnt(8)
.Lrw_out_1:
	s_waitcnt lgkmcnt(0)
	s_barrier
	s_setprio 1
	s_waitcnt lgkmcnt(0)
	v_mfma_f32_16x16x32_bf16 v[142:145], v[66:69], v[162:165], v[142:145]
	v_mfma_f32_16x16x32_bf16 v[138:141], v[74:77], v[162:165], v[138:141]
	v_mfma_f32_16x16x32_bf16 v[126:129], v[66:69], v[170:173], v[126:129]
	v_mfma_f32_16x16x32_bf16 v[122:125], v[74:77], v[170:173], v[122:125]
	v_mfma_f32_16x16x32_bf16 v[110:113], v[66:69], v[178:181], v[110:113]
	v_mfma_f32_16x16x32_bf16 v[106:109], v[74:77], v[178:181], v[106:109]
	v_mfma_f32_16x16x32_bf16 v[94:97], v[66:69], v[186:189], v[94:97]
	v_mfma_f32_16x16x32_bf16 v[90:93], v[74:77], v[186:189], v[90:93]
	v_mfma_f32_16x16x32_bf16 v[142:145], v[70:73], v[166:169], v[142:145]
	v_mfma_f32_16x16x32_bf16 v[138:141], v[78:81], v[166:169], v[138:141]
	v_mfma_f32_16x16x32_bf16 v[126:129], v[70:73], v[174:177], v[126:129]
	v_mfma_f32_16x16x32_bf16 v[122:125], v[78:81], v[174:177], v[122:125]
	v_mfma_f32_16x16x32_bf16 v[110:113], v[70:73], v[182:185], v[110:113]
	v_mfma_f32_16x16x32_bf16 v[106:109], v[78:81], v[182:185], v[106:109]
	v_mfma_f32_16x16x32_bf16 v[94:97], v[70:73], v[190:193], v[94:97]
	v_mfma_f32_16x16x32_bf16 v[90:93], v[78:81], v[190:193], v[90:93]
	s_setprio 0
	s_setprio 1
	v_mfma_f32_16x16x32_bf16 v[134:137], v[146:149], v[162:165], v[134:137]
	v_mfma_f32_16x16x32_bf16 v[130:133], v[154:157], v[162:165], v[130:133]
	v_mfma_f32_16x16x32_bf16 v[118:121], v[146:149], v[170:173], v[118:121]
	v_mfma_f32_16x16x32_bf16 v[114:117], v[154:157], v[170:173], v[114:117]
	v_mfma_f32_16x16x32_bf16 v[102:105], v[146:149], v[178:181], v[102:105]
	v_mfma_f32_16x16x32_bf16 v[98:101], v[154:157], v[178:181], v[98:101]
	v_mfma_f32_16x16x32_bf16 v[86:89], v[146:149], v[186:189], v[86:89]
	v_mfma_f32_16x16x32_bf16 v[82:85], v[154:157], v[186:189], v[82:85]
	v_mfma_f32_16x16x32_bf16 v[134:137], v[150:153], v[166:169], v[134:137]
	v_mfma_f32_16x16x32_bf16 v[130:133], v[158:161], v[166:169], v[130:133]
	v_mfma_f32_16x16x32_bf16 v[118:121], v[150:153], v[174:177], v[118:121]
	v_mfma_f32_16x16x32_bf16 v[114:117], v[158:161], v[174:177], v[114:117]
	v_mfma_f32_16x16x32_bf16 v[102:105], v[150:153], v[182:185], v[102:105]
	v_mfma_f32_16x16x32_bf16 v[98:101], v[158:161], v[182:185], v[98:101]
	v_mfma_f32_16x16x32_bf16 v[86:89], v[150:153], v[190:193], v[86:89]
	v_mfma_f32_16x16x32_bf16 v[82:85], v[158:161], v[190:193], v[82:85]
	s_setprio 0
	s_barrier
	s_add_i32 s75, s75, s41
	v_lshl_add_u64 v[194:195], s[36:37], 0, v[222:223]
	s_mov_b32 m0, s75
	ds_read_b128 v[162:165], v211 offset:16384
	ds_read_b128 v[166:169], v211 offset:17408
	ds_read_b128 v[170:173], v211 offset:18432
	ds_read_b128 v[174:177], v211 offset:19456
	ds_read_b128 v[178:181], v211 offset:20480
	ds_read_b128 v[182:185], v211 offset:21504
	ds_read_b128 v[186:189], v211 offset:22528
	ds_read_b128 v[190:193], v211 offset:23552
	global_load_lds_dwordx4 v[194:195], off
	s_add_i32 m0, s75, 0x2000
	s_add_u32 s76, s36, 0x40000
	v_lshl_add_u64 v[196:197], s[36:37], 0, v[226:227]
	s_addc_u32 s77, s37, 0
	s_add_i32 s75, s78, s41
	global_load_lds_dwordx4 v[196:197], off
	v_lshl_add_u64 v[198:199], s[76:77], 0, v[222:223]
	s_mov_b32 m0, s75
	v_lshl_add_u64 v[200:201], s[38:39], 0, v[224:225]
	global_load_lds_dwordx4 v[198:199], off
	v_lshl_add_u64 v[198:199], s[76:77], 0, v[226:227]
	s_add_i32 m0, s75, 0x2000
	s_nop 0
	global_load_lds_dwordx4 v[198:199], off
	v_lshl_add_u64 v[198:199], s[38:39], 0, v[220:221]
	s_mov_b32 m0, s27
	s_nop 0
	global_load_lds_dwordx4 v[198:199], off
	s_mov_b32 m0, s60
	s_nop 0
	global_load_lds_dwordx4 v[200:201], off
	s_cmp_lg_u32 s98, 0
	s_cbranch_scc1 .Lrw_out_2
	s_waitcnt vmcnt(8)
; #define PG8_STAGE(bufoff, gbase, voff) do { _Pragma("unroll") for (int _i = 0; _i < 2; ++_i) \
;         __builtin_amdgcn_global_load_lds((const unsigned*)((const char*)(gbase) + (voff)[_i]), (PG8_LAS unsigned*)(lds + (bufoff) + ldsw + _i * 8192), 16, 0, 0); } while (0)
; #define PG8_LDA(dst, b, h) do { _Pragma("unroll") for (int m = 0; m < 4; ++m) _Pragma("unroll") for (int k = 0; k < 2; ++k) dst[m][k] = *(const PG8_LAS bf16x8*)(lds + PG8_SA(b, h) + aoff + m * 2048 + k * 1024); } while (0)
; #define PG8_LDB(dst, b, h) do { _Pragma("unroll") for (int n = 0; n < 2; ++n) _Pragma("unroll") for (int k = 0; k < 2; ++k) dst[n][k] = *(const PG8_LAS bf16x8*)(lds + PG8_SB(b, h) + boff + n * 2048 + k * 1024); } while (0)
; #define PG8_MMA(ai, bj, At, Bt) do { __builtin_amdgcn_s_setprio(1); _Pragma("unroll") for (int m = 0; m < 4; ++m) _Pragma("unroll") for (int n = 0; n < 2; ++n) _Pragma("unroll") for (int k = 0; k < 2; ++k) \
;         acc[ai][bj][m][n] = __builtin_amdgcn_mfma_f32_16x16x32_bf16(Bt[n][k], At[m][k], acc[ai][bj][m][n], 0, 0, 0); __builtin_amdgcn_s_setprio(0); } while (0)
; #define PG8_WAIT_V(n) asm volatile("s_waitcnt vmcnt(" #n ")" ::: "memory")
; #define PG8_WAIT_L(n) asm volatile("s_waitcnt lgkmcnt(" #n ")" ::: "memory")
; #define PG8_BAR __builtin_amdgcn_s_barrier()
; #define PG8_SCHED __builtin_amdgcn_sched_barrier(0)
; template <class Epi, class Sched, bool ALIGN_EPI = false, bool SP2 = false>
; __device__ __forceinline__ void gemm_phase(PG8_LAS unsigned char* lds, const Gemm g, const Sched& S, const Epi& E) {
;     ...
;             PG8_WAIT_V(8); PG8_WAIT_L(0); PG8_BAR; PG8_MMA(1, 0, At, B0); PG8_MMA(1, 1, At, B1); PG8_BAR; PG8_SCHED;
;             PG8_LDB(B0, 1, 0); PG8_LDB(B1, 1, 1); PG8_SCHED; PG8_LDA(At, 1, 0); PG8_STAGE(PG8_SA(0, 1), a2 + hstep, voffA);
;             PG8_WAIT_V(8); PG8_WAIT_L(0); PG8_BAR; PG8_MMA(0, 0, At, B0); PG8_MMA(0, 1, At, B1); PG8_BAR; PG8_SCHED;
.Lrw_out_2:
	s_mov_b32 s98, 0
	s_waitcnt lgkmcnt(0)
	s_barrier
	s_setprio 1
	s_waitcnt lgkmcnt(0)
	v_mfma_f32_16x16x32_bf16 v[62:65], v[66:69], v[162:165], v[62:65]
	v_mfma_f32_16x16x32_bf16 v[58:61], v[74:77], v[162:165], v[58:61]
	v_mfma_f32_16x16x32_bf16 v[46:49], v[66:69], v[170:173], v[46:49]
	v_mfma_f32_16x16x32_bf16 v[42:45], v[74:77], v[170:173], v[42:45]
	v_mfma_f32_16x16x32_bf16 v[30:33], v[66:69], v[178:181], v[30:33]
	v_mfma_f32_16x16x32_bf16 v[26:29], v[74:77], v[178:181], v[26:29]
	v_mfma_f32_16x16x32_bf16 v[14:17], v[66:69], v[186:189], v[14:17]
	v_mfma_f32_16x16x32_bf16 v[10:13], v[74:77], v[186:189], v[10:13]
	v_mfma_f32_16x16x32_bf16 v[62:65], v[70:73], v[166:169], v[62:65]
	v_mfma_f32_16x16x32_bf16 v[58:61], v[78:81], v[166:169], v[58:61]
	v_mfma_f32_16x16x32_bf16 v[46:49], v[70:73], v[174:177], v[46:49]
	v_mfma_f32_16x16x32_bf16 v[42:45], v[78:81], v[174:177], v[42:45]
	v_mfma_f32_16x16x32_bf16 v[30:33], v[70:73], v[182:185], v[30:33]
	v_mfma_f32_16x16x32_bf16 v[26:29], v[78:81], v[182:185], v[26:29]
	v_mfma_f32_16x16x32_bf16 v[14:17], v[70:73], v[190:193], v[14:17]
	v_mfma_f32_16x16x32_bf16 v[10:13], v[78:81], v[190:193], v[10:13]
	s_setprio 0
	s_setprio 1
	v_mfma_f32_16x16x32_bf16 v[54:57], v[146:149], v[162:165], v[54:57]
	v_mfma_f32_16x16x32_bf16 v[50:53], v[154:157], v[162:165], v[50:53]
	v_mfma_f32_16x16x32_bf16 v[38:41], v[146:149], v[170:173], v[38:41]
	v_mfma_f32_16x16x32_bf16 v[34:37], v[154:157], v[170:173], v[34:37]
	v_mfma_f32_16x16x32_bf16 v[22:25], v[146:149], v[178:181], v[22:25]
	v_mfma_f32_16x16x32_bf16 v[18:21], v[154:157], v[178:181], v[18:21]
	v_mfma_f32_16x16x32_bf16 v[6:9], v[146:149], v[186:189], v[6:9]
	v_mfma_f32_16x16x32_bf16 v[2:5], v[154:157], v[186:189], v[2:5]
	v_mfma_f32_16x16x32_bf16 v[54:57], v[150:153], v[166:169], v[54:57]
	v_mfma_f32_16x16x32_bf16 v[50:53], v[158:161], v[166:169], v[50:53]
	v_mfma_f32_16x16x32_bf16 v[38:41], v[150:153], v[174:177], v[38:41]
	v_mfma_f32_16x16x32_bf16 v[34:37], v[158:161], v[174:177], v[34:37]
	v_mfma_f32_16x16x32_bf16 v[22:25], v[150:153], v[182:185], v[22:25]
	v_mfma_f32_16x16x32_bf16 v[18:21], v[158:161], v[182:185], v[18:21]
	v_mfma_f32_16x16x32_bf16 v[6:9], v[150:153], v[190:193], v[6:9]
	v_mfma_f32_16x16x32_bf16 v[2:5], v[158:161], v[190:193], v[2:5]
	s_setprio 0
	s_barrier
	s_add_i32 s75, 0, 0x18000
	v_add_u32_e32 v0, s75, v210
	s_add_i32 s76, 0, 0x1c000
	ds_read_b128 v[66:69], v0
	ds_read_b128 v[70:73], v0 offset:1024
	ds_read_b128 v[74:77], v0 offset:2048
	ds_read_b128 v[78:81], v0 offset:3072
	v_add_u32_e32 v0, s76, v210
	ds_read_b128 v[146:149], v0
	ds_read_b128 v[150:153], v0 offset:1024
	ds_read_b128 v[154:157], v0 offset:2048
	ds_read_b128 v[158:161], v0 offset:3072
	s_add_u32 s38, s38, 0x40000
	s_addc_u32 s39, s39, 0
	s_mov_b32 m0, s61
	v_lshl_add_u64 v[202:203], s[38:39], 0, v[220:221]
	ds_read_b128 v[162:165], v211 offset:32768
	ds_read_b128 v[166:169], v211 offset:33792
	ds_read_b128 v[170:173], v211 offset:34816
	ds_read_b128 v[174:177], v211 offset:35840
	ds_read_b128 v[178:181], v211 offset:36864
	ds_read_b128 v[182:185], v211 offset:37888
	ds_read_b128 v[186:189], v211 offset:38912
	ds_read_b128 v[190:193], v211 offset:39936
	global_load_lds_dwordx4 v[202:203], off
	v_lshl_add_u64 v[202:203], s[38:39], 0, v[224:225]
	s_mov_b32 m0, s62
	s_nop 0
	global_load_lds_dwordx4 v[202:203], off
	s_waitcnt vmcnt(8)
	s_waitcnt lgkmcnt(0)
	s_barrier
	s_setprio 1
	s_waitcnt lgkmcnt(0)
	v_mfma_f32_16x16x32_bf16 v[142:145], v[66:69], v[162:165], v[142:145]
	v_mfma_f32_16x16x32_bf16 v[138:141], v[74:77], v[162:165], v[138:141]
	v_mfma_f32_16x16x32_bf16 v[126:129], v[66:69], v[170:173], v[126:129]
	v_mfma_f32_16x16x32_bf16 v[122:125], v[74:77], v[170:173], v[122:125]
	v_mfma_f32_16x16x32_bf16 v[110:113], v[66:69], v[178:181], v[110:113]
	v_mfma_f32_16x16x32_bf16 v[106:109], v[74:77], v[178:181], v[106:109]
	v_mfma_f32_16x16x32_bf16 v[94:97], v[66:69], v[186:189], v[94:97]
	v_mfma_f32_16x16x32_bf16 v[90:93], v[74:77], v[186:189], v[90:93]
	v_mfma_f32_16x16x32_bf16 v[142:145], v[70:73], v[166:169], v[142:145]
	v_mfma_f32_16x16x32_bf16 v[138:141], v[78:81], v[166:169], v[138:141]
	v_mfma_f32_16x16x32_bf16 v[126:129], v[70:73], v[174:177], v[126:129]
	v_mfma_f32_16x16x32_bf16 v[122:125], v[78:81], v[174:177], v[122:125]
	v_mfma_f32_16x16x32_bf16 v[110:113], v[70:73], v[182:185], v[110:113]
	v_mfma_f32_16x16x32_bf16 v[106:109], v[78:81], v[182:185], v[106:109]
	v_mfma_f32_16x16x32_bf16 v[94:97], v[70:73], v[190:193], v[94:97]
	v_mfma_f32_16x16x32_bf16 v[90:93], v[78:81], v[190:193], v[90:93]
	s_setprio 0
	s_setprio 1
	v_mfma_f32_16x16x32_bf16 v[134:137], v[146:149], v[162:165], v[134:137]
	v_mfma_f32_16x16x32_bf16 v[130:133], v[154:157], v[162:165], v[130:133]
	v_mfma_f32_16x16x32_bf16 v[118:121], v[146:149], v[170:173], v[118:121]
	v_mfma_f32_16x16x32_bf16 v[114:117], v[154:157], v[170:173], v[114:117]
	v_mfma_f32_16x16x32_bf16 v[102:105], v[146:149], v[178:181], v[102:105]
	v_mfma_f32_16x16x32_bf16 v[98:101], v[154:157], v[178:181], v[98:101]
	v_mfma_f32_16x16x32_bf16 v[86:89], v[146:149], v[186:189], v[86:89]
	v_mfma_f32_16x16x32_bf16 v[82:85], v[154:157], v[186:189], v[82:85]
	v_mfma_f32_16x16x32_bf16 v[134:137], v[150:153], v[166:169], v[134:137]
	v_mfma_f32_16x16x32_bf16 v[130:133], v[158:161], v[166:169], v[130:133]
	v_mfma_f32_16x16x32_bf16 v[118:121], v[150:153], v[174:177], v[118:121]
	v_mfma_f32_16x16x32_bf16 v[114:117], v[158:161], v[174:177], v[114:117]
	v_mfma_f32_16x16x32_bf16 v[102:105], v[150:153], v[182:185], v[102:105]
	v_mfma_f32_16x16x32_bf16 v[98:101], v[158:161], v[182:185], v[98:101]
	v_mfma_f32_16x16x32_bf16 v[86:89], v[150:153], v[190:193], v[86:89]
	v_mfma_f32_16x16x32_bf16 v[82:85], v[158:161], v[190:193], v[82:85]
	s_setprio 0
	s_barrier
; #define PG8_STAGE(bufoff, gbase, voff) do { _Pragma("unroll") for (int _i = 0; _i < 2; ++_i) \
;         __builtin_amdgcn_global_load_lds((const unsigned*)((const char*)(gbase) + (voff)[_i]), (PG8_LAS unsigned*)(lds + (bufoff) + ldsw + _i * 8192), 16, 0, 0); } while (0)
; #define PG8_LDA(dst, b, h) do { _Pragma("unroll") for (int m = 0; m < 4; ++m) _Pragma("unroll") for (int k = 0; k < 2; ++k) dst[m][k] = *(const PG8_LAS bf16x8*)(lds + PG8_SA(b, h) + aoff + m * 2048 + k * 1024); } while (0)
; #define PG8_WAIT_V(n) asm volatile("s_waitcnt vmcnt(" #n ")" ::: "memory")
; template <class Epi, class Sched, bool ALIGN_EPI = false, bool SP2 = false>
; __device__ __forceinline__ void gemm_phase(PG8_LAS unsigned char* lds, const Gemm g, const Sched& S, const Epi& E) {
;     ...
;             PG8_LDA(At, 1, 1); PG8_STAGE(PG8_SB(1, 0), b3, voffB); PG8_STAGE(PG8_SB(1, 1), b3 + hstep, voffB); PG8_STAGE(PG8_SA(1, 0), a3, voffA);
;             PG8_WAIT_V(8); PG8_WAIT_L(0); PG8_BAR; PG8_MMA(1, 0, At, B0); PG8_MMA(1, 1, At, B1); PG8_BAR; PG8_SCHED;
;             } else {
;             PG8_LDB(B0, 0, 0); PG8_SCHED; PG8_LDA(At, 0, 0); PG8_STAGE(PG8_SA(1, 1), a1 + hstep, voffA);
;             PG8_WAIT_L(8); PG8_BAR; PG8_WAIT_L(0); PG8_MMA(0, 0, At, B0); PG8_BAR; PG8_SCHED;
;             PG8_LDB(B1, 0, 1); PG8_STAGE(PG8_SB(0, 0), b2, voffB);
;             PG8_BAR; PG8_WAIT_L(0); PG8_MMA(0, 1, At, B1); PG8_BAR;
;             PG8_LDA(At, 0, 1); PG8_STAGE(PG8_SA(0, 0), a2, voffA);
;             PG8_BAR; PG8_WAIT_L(0); PG8_MMA(1, 0, At, B0); PG8_BAR; PG8_SCHED;
;             PG8_STAGE(PG8_SB(0, 1), b2 + hstep, voffB);
;             PG8_WAIT_V(6); PG8_BAR; PG8_MMA(1, 1, At, B1); PG8_BAR;
;             PG8_LDB(B0, 1, 0); PG8_SCHED; PG8_LDA(At, 1, 0); PG8_STAGE(PG8_SA(0, 1), a2 + hstep, voffA);
;             PG8_WAIT_L(8); PG8_BAR; PG8_WAIT_L(0); PG8_MMA(0, 0, At, B0); PG8_BAR; PG8_SCHED;
;             PG8_LDB(B1, 1, 1); PG8_STAGE(PG8_SB(1, 0), b3, voffB);
;             PG8_BAR; PG8_WAIT_L(0); PG8_MMA(0, 1, At, B1); PG8_BAR;
;             PG8_LDA(At, 1, 1); PG8_STAGE(PG8_SA(1, 0), a3, voffA);
;             PG8_BAR; PG8_WAIT_L(0); PG8_MMA(1, 0, At, B0); PG8_BAR; PG8_SCHED;
;             PG8_STAGE(PG8_SB(1, 1), b3 + hstep, voffB);
;             PG8_WAIT_V(6); PG8_BAR; PG8_MMA(1, 1, At, B1); PG8_BAR;
;             }
;         }
;         if constexpr (ALIGN_EPI) { if (wr == 0) PG8_BAR; }
	s_add_i32 s38, s75, s41
	v_lshl_add_u64 v[194:195], v[194:195], 0, s[28:29]
	s_mov_b32 m0, s38
	ds_read_b128 v[162:165], v211 offset:49152
	ds_read_b128 v[166:169], v211 offset:50176
	ds_read_b128 v[170:173], v211 offset:51200
	ds_read_b128 v[174:177], v211 offset:52224
	ds_read_b128 v[178:181], v211 offset:53248
	ds_read_b128 v[182:185], v211 offset:54272
	ds_read_b128 v[186:189], v211 offset:55296
	ds_read_b128 v[190:193], v211 offset:56320
	global_load_lds_dwordx4 v[194:195], off
	s_add_i32 m0, s38, 0x2000
	s_add_u32 s36, s36, 0x40080
	v_lshl_add_u64 v[194:195], v[196:197], 0, s[28:29]
	s_addc_u32 s37, s37, 0
	s_add_i32 s38, s76, s41
	global_load_lds_dwordx4 v[194:195], off
	v_lshl_add_u64 v[194:195], s[36:37], 0, v[222:223]
	s_mov_b32 m0, s38
	s_nop 0
	global_load_lds_dwordx4 v[194:195], off
	v_lshl_add_u64 v[194:195], s[36:37], 0, v[226:227]
	s_add_i32 m0, s38, 0x2000
	s_nop 0
	global_load_lds_dwordx4 v[194:195], off
	v_lshl_add_u64 v[194:195], v[198:199], 0, s[28:29]
	s_mov_b32 m0, s65
	s_nop 0
	global_load_lds_dwordx4 v[194:195], off
	v_lshl_add_u64 v[194:195], v[200:201], 0, s[28:29]
	s_mov_b32 m0, s69
	s_nop 0
	global_load_lds_dwordx4 v[194:195], off
	s_waitcnt vmcnt(8)
	s_waitcnt lgkmcnt(0)
	s_barrier
	s_setprio 1
	s_waitcnt lgkmcnt(0)
	v_mfma_f32_16x16x32_bf16 v[62:65], v[66:69], v[162:165], v[62:65]
	v_mfma_f32_16x16x32_bf16 v[58:61], v[74:77], v[162:165], v[58:61]
	v_mfma_f32_16x16x32_bf16 v[46:49], v[66:69], v[170:173], v[46:49]
	v_mfma_f32_16x16x32_bf16 v[42:45], v[74:77], v[170:173], v[42:45]
	v_mfma_f32_16x16x32_bf16 v[30:33], v[66:69], v[178:181], v[30:33]
	v_mfma_f32_16x16x32_bf16 v[26:29], v[74:77], v[178:181], v[26:29]
	v_mfma_f32_16x16x32_bf16 v[14:17], v[66:69], v[186:189], v[14:17]
	v_mfma_f32_16x16x32_bf16 v[10:13], v[74:77], v[186:189], v[10:13]
	v_mfma_f32_16x16x32_bf16 v[62:65], v[70:73], v[166:169], v[62:65]
	v_mfma_f32_16x16x32_bf16 v[58:61], v[78:81], v[166:169], v[58:61]
	v_mfma_f32_16x16x32_bf16 v[46:49], v[70:73], v[174:177], v[46:49]
	v_mfma_f32_16x16x32_bf16 v[42:45], v[78:81], v[174:177], v[42:45]
	v_mfma_f32_16x16x32_bf16 v[30:33], v[70:73], v[182:185], v[30:33]
	v_mfma_f32_16x16x32_bf16 v[26:29], v[78:81], v[182:185], v[26:29]
	v_mfma_f32_16x16x32_bf16 v[14:17], v[70:73], v[190:193], v[14:17]
	v_mfma_f32_16x16x32_bf16 v[10:13], v[78:81], v[190:193], v[10:13]
	s_setprio 0
	s_setprio 1
	v_mfma_f32_16x16x32_bf16 v[54:57], v[146:149], v[162:165], v[54:57]
	v_mfma_f32_16x16x32_bf16 v[50:53], v[154:157], v[162:165], v[50:53]
	v_mfma_f32_16x16x32_bf16 v[38:41], v[146:149], v[170:173], v[38:41]
	v_mfma_f32_16x16x32_bf16 v[34:37], v[154:157], v[170:173], v[34:37]
	v_mfma_f32_16x16x32_bf16 v[22:25], v[146:149], v[178:181], v[22:25]
	v_mfma_f32_16x16x32_bf16 v[18:21], v[154:157], v[178:181], v[18:21]
	v_mfma_f32_16x16x32_bf16 v[6:9], v[146:149], v[186:189], v[6:9]
	v_mfma_f32_16x16x32_bf16 v[2:5], v[154:157], v[186:189], v[2:5]
	v_mfma_f32_16x16x32_bf16 v[54:57], v[150:153], v[166:169], v[54:57]
	v_mfma_f32_16x16x32_bf16 v[50:53], v[158:161], v[166:169], v[50:53]
	v_mfma_f32_16x16x32_bf16 v[38:41], v[150:153], v[174:177], v[38:41]
	v_mfma_f32_16x16x32_bf16 v[34:37], v[158:161], v[174:177], v[34:37]
	v_mfma_f32_16x16x32_bf16 v[22:25], v[150:153], v[182:185], v[22:25]
	v_mfma_f32_16x16x32_bf16 v[18:21], v[158:161], v[182:185], v[18:21]
	v_mfma_f32_16x16x32_bf16 v[6:9], v[150:153], v[190:193], v[6:9]
	v_mfma_f32_16x16x32_bf16 v[2:5], v[158:161], v[190:193], v[2:5]
	s_setprio 0
	s_barrier
	s_add_i32 s74, s74, 2
	s_add_u32 s72, s72, 0x100
	s_addc_u32 s73, s73, 0
	s_add_u32 s52, s52, 0x100
	s_addc_u32 s53, s53, 0
	s_cmp_gt_u32 s74, 13
	s_cbranch_scc0 .LBB0_1079
	s_and_b64 vcc, exec, s[14:15]
	s_cbranch_vccz .LBB0_1082
	s_barrier

; #define PG8_BAR __builtin_amdgcn_s_barrier()
; template <class Epi, class Sched, bool ALIGN_EPI = false, bool SP2 = false>
; __device__ __forceinline__ void gemm_phase(PG8_LAS unsigned char* lds, const Gemm g, const Sched& S, const Epi& E) {
;     ...
;         if constexpr (!Epi::AFTER_DRAIN) { E(acc, cur, wr, wc, fr, fq); S.done(cur); }
;         if (!has_next) break;
; #pragma unroll
;         for (int a = 0; a < 2; ++a)
; #pragma unroll
;             for (int b = 0; b < 2; ++b)
; #pragma unroll
;                 for (int m = 0; m < 4; ++m)
; #pragma unroll
;                     for (int n = 0; n < 2; ++n) acc[a][b][m][n] = (f32x4){0.f, 0.f, 0.f, 0.f};
;         cur = nxt; cA = nA; cB = nB; ++ui;
;         if constexpr (ALIGN_EPI) { if (wr == 1) PG8_BAR; }
;     }
.LBB0_1130:
	s_or_b64 exec, exec, s[4:5]
	s_andn2_b64 vcc, exec, s[0:1]
	s_mov_b64 s[0:1], -1
	s_mov_b32 s98, 1
	s_cbranch_vccnz .LBB0_1071
	s_andn2_b64 vcc, exec, s[6:7]
	s_cbranch_vccnz .LBB0_1070
	s_barrier
	s_branch .LBB0_1070
